# RG-LRU scan: v_sqrt_f32 instead of the correctly-rounded sqrtf expansion (f32, 1 ulp)
# speedup vs baseline: 1.0301x; 1.0100x over previous
; __device__ __forceinline__ f32x4 unpack4(u32x2 u) { return (f32x4){__uint_as_float(u.x << 16), __uint_as_float(u.x & 0xffff0000u), __uint_as_float(u.y << 16), __uint_as_float(u.y & 0xffff0000u)}; }
; template <int ph>
; __device__ __forceinline__ void run_phase(const Args& args, LAS unsigned char* lds, const int G, const int bx, const bool fin = true) {
;     ...
;             auto lru_ab = [](f32x4 gr, f32x4 gi, f32x4 xc, f32x4 sp, f32x4& a, f32x4& bb) {
;                 const f32x4 la = gr * sp; a = (f32x4){__expf(la[0]), __expf(la[1]), __expf(la[2]), __expf(la[3])};
;                 const f32x4 om = (f32x4){1.f, 1.f, 1.f, 1.f} - a * a;
;                 bb = (f32x4){sqrtf(fmaxf(om[0], 0.f)), sqrtf(fmaxf(om[1], 0.f)), sqrtf(fmaxf(om[2], 0.f)), sqrtf(fmaxf(om[3], 0.f))} * gi * xc; };
;     ...
; #pragma unroll 8
;                 for (int t = 0; t < 32; ++t) { const size_t o = base + (size_t)t * D;
;                     const u32x4 gr = *(const u32x4*)(GR + o), gi = *(const u32x4*)(GI + o), xc = *(const u32x4*)(XC + o);
;                     f32x4 a, bb;
;                     lru_ab(unpack4((u32x2){gr.x, gr.y}), unpack4((u32x2){gi.x, gi.y}), unpack4((u32x2){xc.x, xc.y}), sp0, a, bb); A0 = A0 * a; B0 = a * B0 + bb;
;                     lru_ab(unpack4((u32x2){gr.z, gr.w}), unpack4((u32x2){gi.z, gi.w}), unpack4((u32x2){xc.z, xc.w}), sp1, a, bb); A1 = A1 * a; B1 = a * B1 + bb; }
.LBB0_1061:
	v_lshl_add_u64 v[18:19], v[34:35], 0, s[24:25]
	v_add_co_u32_e32 v62, vcc, s46, v18
	s_add_u32 s24, s24, 0x4000
	s_nop 0
	v_addc_co_u32_e32 v63, vcc, 0, v19, vcc
	v_add_co_u32_e32 v20, vcc, s52, v18
	s_addc_u32 s25, s25, 0
	s_nop 0
	v_addc_co_u32_e32 v21, vcc, 0, v19, vcc
	global_load_dwordx4 v[40:43], v[20:21], off offset:-4096
	v_add_co_u32_e32 v64, vcc, s47, v18
	s_cmp_eq_u32 s24, 0x10000
	s_nop 0
	v_addc_co_u32_e32 v65, vcc, 0, v19, vcc
	v_add_co_u32_e32 v36, vcc, s53, v18
	s_nop 1
	v_addc_co_u32_e32 v37, vcc, 0, v19, vcc
	v_add_co_u32_e32 v66, vcc, s48, v18
	global_load_dwordx4 v[44:47], v[36:37], off offset:-4096
	s_nop 0
	v_addc_co_u32_e32 v67, vcc, 0, v19, vcc
	v_add_co_u32_e32 v38, vcc, s54, v18
	s_waitcnt vmcnt(1)
	v_lshlrev_b32_e32 v70, 16, v40
	v_addc_co_u32_e32 v39, vcc, 0, v19, vcc
	global_load_dwordx4 v[48:51], v[38:39], off offset:-4096
	v_and_b32_e32 v71, 0xffff0000, v40
	v_pk_mul_f32 v[70:71], v[28:29], v[70:71]
	v_lshlrev_b32_e32 v40, 16, v41
	v_mul_f32_e32 v1, 0x3fb8aa3b, v70
	v_exp_f32_e32 v70, v1
	v_mul_f32_e32 v1, 0x3fb8aa3b, v71
	v_exp_f32_e32 v71, v1
	v_and_b32_e32 v41, 0xffff0000, v41
	v_pk_mul_f32 v[40:41], v[26:27], v[40:41]
	v_xor_b32_e32 v78, 0x80000000, v70
	v_mul_f32_e32 v1, 0x3fb8aa3b, v40
	v_xor_b32_e32 v79, 0x80000000, v71
	v_exp_f32_e32 v40, v1
	v_mul_f32_e32 v1, 0x3fb8aa3b, v41
	v_pk_fma_f32 v[78:79], v[78:79], v[70:71], 1.0 op_sel_hi:[1,1,0]
	v_exp_f32_e32 v41, v1
	v_max_f32_e32 v1, 0, v78
	v_xor_b32_e32 v77, 0x80000000, v41
	v_xor_b32_e32 v76, 0x80000000, v40
	v_pk_fma_f32 v[76:77], v[76:77], v[40:41], 1.0 op_sel_hi:[1,1,0]
	s_waitcnt vmcnt(1)
	v_lshlrev_b32_e32 v72, 16, v44
	v_and_b32_e32 v73, 0xffff0000, v44
	v_lshlrev_b32_e32 v44, 16, v45
	v_and_b32_e32 v45, 0xffff0000, v45
	s_waitcnt vmcnt(0)
	v_lshlrev_b32_e32 v74, 16, v48
	v_sqrt_f32_e32 v78, v1
	v_max_f32_e32 v1, 0, v79
	v_and_b32_e32 v75, 0xffff0000, v48
	v_lshlrev_b32_e32 v48, 16, v49
	v_and_b32_e32 v49, 0xffff0000, v49
	v_sqrt_f32_e32 v79, v1
	v_max_f32_e32 v1, 0, v76
	v_pk_mul_f32 v[72:73], v[78:79], v[72:73]
	v_sqrt_f32_e32 v76, v1
	v_max_f32_e32 v1, 0, v77
	v_sqrt_f32_e32 v77, v1
	s_nop 0
	v_pk_mul_f32 v[44:45], v[76:77], v[44:45]
	s_nop 0
	v_pk_mul_f32 v[44:45], v[44:45], v[48:49]
	v_pk_mul_f32 v[48:49], v[72:73], v[74:75]
	v_pk_mul_f32 v[74:75], v[8:9], v[40:41]
	v_pk_fma_f32 v[48:49], v[2:3], v[70:71], v[48:49]
	v_lshlrev_b32_e32 v2, 16, v42
	v_and_b32_e32 v3, 0xffff0000, v42
	v_pk_mul_f32 v[2:3], v[32:33], v[2:3]
	v_pk_fma_f32 v[40:41], v[4:5], v[40:41], v[44:45]
	v_mul_f32_e32 v1, 0x3fb8aa3b, v2
	v_exp_f32_e32 v2, v1
	v_mul_f32_e32 v1, 0x3fb8aa3b, v3
	v_exp_f32_e32 v3, v1
	v_lshlrev_b32_e32 v4, 16, v43
	v_and_b32_e32 v5, 0xffff0000, v43
	v_pk_mul_f32 v[4:5], v[30:31], v[4:5]
	v_lshlrev_b32_e32 v42, 16, v50
	v_and_b32_e32 v43, 0xffff0000, v50
	v_lshlrev_b32_e32 v44, 16, v51
	v_and_b32_e32 v45, 0xffff0000, v51
	v_mul_f32_e32 v1, 0x3fb8aa3b, v4
	v_xor_b32_e32 v51, 0x80000000, v3
	v_xor_b32_e32 v50, 0x80000000, v2
	v_exp_f32_e32 v4, v1
	v_mul_f32_e32 v1, 0x3fb8aa3b, v5
	v_pk_fma_f32 v[50:51], v[50:51], v[2:3], 1.0 op_sel_hi:[1,1,0]
	v_exp_f32_e32 v5, v1
	v_max_f32_e32 v1, 0, v50
	v_pk_mul_f32 v[72:73], v[6:7], v[70:71]
	v_lshlrev_b32_e32 v6, 16, v46
	v_and_b32_e32 v7, 0xffff0000, v46
	v_lshlrev_b32_e32 v8, 16, v47
	v_and_b32_e32 v9, 0xffff0000, v47
	v_xor_b32_e32 v47, 0x80000000, v5
	v_xor_b32_e32 v46, 0x80000000, v4
	v_pk_fma_f32 v[46:47], v[46:47], v[4:5], 1.0 op_sel_hi:[1,1,0]
	s_nop 0
	v_sqrt_f32_e32 v50, v1
	v_max_f32_e32 v1, 0, v51
	v_sqrt_f32_e32 v51, v1
	v_max_f32_e32 v1, 0, v46
	v_pk_mul_f32 v[6:7], v[50:51], v[6:7]
	v_pk_mul_f32 v[6:7], v[6:7], v[42:43]
	v_pk_mul_f32 v[42:43], v[10:11], v[2:3]
	v_pk_fma_f32 v[14:15], v[14:15], v[2:3], v[6:7]
	v_sqrt_f32_e32 v46, v1
	v_max_f32_e32 v1, 0, v47
	v_sqrt_f32_e32 v47, v1
	s_nop 0
	v_pk_mul_f32 v[8:9], v[46:47], v[8:9]
	s_nop 0
	v_pk_mul_f32 v[8:9], v[8:9], v[44:45]
	v_pk_mul_f32 v[44:45], v[12:13], v[4:5]
	v_pk_fma_f32 v[16:17], v[16:17], v[4:5], v[8:9]
	global_load_dwordx4 v[2:5], v[62:63], off offset:2048
	global_load_dwordx4 v[6:9], v[64:65], off offset:2048
	global_load_dwordx4 v[10:13], v[66:67], off offset:2048
	s_waitcnt vmcnt(2)
	v_lshlrev_b32_e32 v46, 16, v2
	v_and_b32_e32 v47, 0xffff0000, v2
	v_pk_mul_f32 v[46:47], v[28:29], v[46:47]
	v_lshlrev_b32_e32 v2, 16, v3
	v_mul_f32_e32 v1, 0x3fb8aa3b, v46
	v_exp_f32_e32 v46, v1
	v_mul_f32_e32 v1, 0x3fb8aa3b, v47
	v_exp_f32_e32 v47, v1
	v_and_b32_e32 v3, 0xffff0000, v3
	v_pk_mul_f32 v[2:3], v[26:27], v[2:3]
	v_xor_b32_e32 v66, 0x80000000, v46
	v_mul_f32_e32 v1, 0x3fb8aa3b, v2
	v_xor_b32_e32 v67, 0x80000000, v47
	v_exp_f32_e32 v2, v1
	v_mul_f32_e32 v1, 0x3fb8aa3b, v3
	v_pk_fma_f32 v[66:67], v[66:67], v[46:47], 1.0 op_sel_hi:[1,1,0]
	v_exp_f32_e32 v3, v1
	v_max_f32_e32 v1, 0, v66
	v_xor_b32_e32 v65, 0x80000000, v3
	v_xor_b32_e32 v64, 0x80000000, v2
	v_pk_fma_f32 v[64:65], v[64:65], v[2:3], 1.0 op_sel_hi:[1,1,0]
	s_waitcnt vmcnt(1)
	v_lshlrev_b32_e32 v50, 16, v6
	v_and_b32_e32 v51, 0xffff0000, v6
	v_lshlrev_b32_e32 v6, 16, v7
	v_and_b32_e32 v7, 0xffff0000, v7
	s_waitcnt vmcnt(0)
; __device__ __forceinline__ f32x4 unpack4(u32x2 u) { return (f32x4){__uint_as_float(u.x << 16), __uint_as_float(u.x & 0xffff0000u), __uint_as_float(u.y << 16), __uint_as_float(u.y & 0xffff0000u)}; }
; template <int ph>
; __device__ __forceinline__ void run_phase(const Args& args, LAS unsigned char* lds, const int G, const int bx, const bool fin = true) {
;     ...
;             auto lru_ab = [](f32x4 gr, f32x4 gi, f32x4 xc, f32x4 sp, f32x4& a, f32x4& bb) {
;                 const f32x4 la = gr * sp; a = (f32x4){__expf(la[0]), __expf(la[1]), __expf(la[2]), __expf(la[3])};
;                 const f32x4 om = (f32x4){1.f, 1.f, 1.f, 1.f} - a * a;
;                 bb = (f32x4){sqrtf(fmaxf(om[0], 0.f)), sqrtf(fmaxf(om[1], 0.f)), sqrtf(fmaxf(om[2], 0.f)), sqrtf(fmaxf(om[3], 0.f))} * gi * xc; };
;     ...
; #pragma unroll 8
;                 for (int t = 0; t < 32; ++t) { const size_t o = base + (size_t)t * D;
;                     const u32x4 gr = *(const u32x4*)(GR + o), gi = *(const u32x4*)(GI + o), xc = *(const u32x4*)(XC + o);
;                     f32x4 a, bb;
;                     lru_ab(unpack4((u32x2){gr.x, gr.y}), unpack4((u32x2){gi.x, gi.y}), unpack4((u32x2){xc.x, xc.y}), sp0, a, bb); A0 = A0 * a; B0 = a * B0 + bb;
;                     lru_ab(unpack4((u32x2){gr.z, gr.w}), unpack4((u32x2){gi.z, gi.w}), unpack4((u32x2){xc.z, xc.w}), sp1, a, bb); A1 = A1 * a; B1 = a * B1 + bb; }
	v_lshlrev_b32_e32 v62, 16, v10
	v_and_b32_e32 v63, 0xffff0000, v10
	v_sqrt_f32_e32 v66, v1
	v_max_f32_e32 v1, 0, v67
	v_lshlrev_b32_e32 v10, 16, v11
	v_and_b32_e32 v11, 0xffff0000, v11
	v_sqrt_f32_e32 v67, v1
	v_max_f32_e32 v1, 0, v64
	v_pk_mul_f32 v[50:51], v[66:67], v[50:51]
	v_pk_mul_f32 v[50:51], v[50:51], v[62:63]
	v_pk_mul_f32 v[62:63], v[74:75], v[2:3]
	v_sqrt_f32_e32 v64, v1
	v_max_f32_e32 v1, 0, v65
	v_sqrt_f32_e32 v65, v1
	s_nop 0
	v_pk_mul_f32 v[6:7], v[64:65], v[6:7]
	v_pk_mul_f32 v[64:65], v[72:73], v[46:47]
	v_pk_mul_f32 v[6:7], v[6:7], v[10:11]
	v_pk_fma_f32 v[46:47], v[48:49], v[46:47], v[50:51]
	v_pk_fma_f32 v[40:41], v[40:41], v[2:3], v[6:7]
	v_lshlrev_b32_e32 v2, 16, v4
	v_and_b32_e32 v3, 0xffff0000, v4
	v_pk_mul_f32 v[2:3], v[32:33], v[2:3]
	v_lshlrev_b32_e32 v4, 16, v5
	v_mul_f32_e32 v1, 0x3fb8aa3b, v2
	v_exp_f32_e32 v2, v1
	v_mul_f32_e32 v1, 0x3fb8aa3b, v3
	v_exp_f32_e32 v3, v1
	v_and_b32_e32 v5, 0xffff0000, v5
	v_pk_mul_f32 v[4:5], v[30:31], v[4:5]
	v_xor_b32_e32 v50, 0x80000000, v2
	v_mul_f32_e32 v1, 0x3fb8aa3b, v4
	v_xor_b32_e32 v51, 0x80000000, v3
	v_exp_f32_e32 v4, v1
	v_mul_f32_e32 v1, 0x3fb8aa3b, v5
	v_pk_fma_f32 v[50:51], v[50:51], v[2:3], 1.0 op_sel_hi:[1,1,0]
	v_exp_f32_e32 v5, v1
	v_max_f32_e32 v1, 0, v50
	v_xor_b32_e32 v49, 0x80000000, v5
	v_xor_b32_e32 v48, 0x80000000, v4
	v_pk_fma_f32 v[48:49], v[48:49], v[4:5], 1.0 op_sel_hi:[1,1,0]
	v_lshlrev_b32_e32 v6, 16, v8
	v_and_b32_e32 v7, 0xffff0000, v8
	v_lshlrev_b32_e32 v8, 16, v9
	v_and_b32_e32 v9, 0xffff0000, v9
	v_lshlrev_b32_e32 v10, 16, v12
	v_and_b32_e32 v11, 0xffff0000, v12
	v_sqrt_f32_e32 v50, v1
	v_max_f32_e32 v1, 0, v51
	v_lshlrev_b32_e32 v12, 16, v13
	v_and_b32_e32 v13, 0xffff0000, v13
	v_pk_mul_f32 v[44:45], v[44:45], v[4:5]
	v_pk_mul_f32 v[42:43], v[42:43], v[2:3]
	v_sqrt_f32_e32 v51, v1
	v_max_f32_e32 v1, 0, v48
	v_pk_mul_f32 v[6:7], v[50:51], v[6:7]
	v_pk_mul_f32 v[6:7], v[6:7], v[10:11]
	v_pk_fma_f32 v[14:15], v[14:15], v[2:3], v[6:7]
	v_sqrt_f32_e32 v48, v1
	v_max_f32_e32 v1, 0, v49
	v_sqrt_f32_e32 v49, v1
	s_nop 0
	v_pk_mul_f32 v[8:9], v[48:49], v[8:9]
	s_nop 0
	v_pk_mul_f32 v[8:9], v[8:9], v[12:13]
	s_nop 0
	v_pk_fma_f32 v[16:17], v[16:17], v[4:5], v[8:9]
	global_load_dwordx4 v[2:5], v[20:21], off
	global_load_dwordx4 v[6:9], v[36:37], off
	global_load_dwordx4 v[10:13], v[38:39], off
	s_waitcnt vmcnt(2)
	v_lshlrev_b32_e32 v48, 16, v2
	v_and_b32_e32 v49, 0xffff0000, v2
	v_pk_mul_f32 v[48:49], v[28:29], v[48:49]
	v_lshlrev_b32_e32 v2, 16, v3
	v_mul_f32_e32 v1, 0x3fb8aa3b, v48
	v_exp_f32_e32 v48, v1
	v_mul_f32_e32 v1, 0x3fb8aa3b, v49
	v_exp_f32_e32 v49, v1
	v_and_b32_e32 v3, 0xffff0000, v3
	v_pk_mul_f32 v[2:3], v[26:27], v[2:3]
	v_xor_b32_e32 v72, 0x80000000, v48
	v_mul_f32_e32 v1, 0x3fb8aa3b, v2
	v_xor_b32_e32 v73, 0x80000000, v49
	v_exp_f32_e32 v2, v1
	v_mul_f32_e32 v1, 0x3fb8aa3b, v3
	v_pk_fma_f32 v[72:73], v[72:73], v[48:49], 1.0 op_sel_hi:[1,1,0]
	v_exp_f32_e32 v3, v1
	v_max_f32_e32 v1, 0, v72
	v_xor_b32_e32 v71, 0x80000000, v3
	v_xor_b32_e32 v70, 0x80000000, v2
	v_pk_fma_f32 v[70:71], v[70:71], v[2:3], 1.0 op_sel_hi:[1,1,0]
	s_waitcnt vmcnt(1)
	v_lshlrev_b32_e32 v50, 16, v6
	v_and_b32_e32 v51, 0xffff0000, v6
	v_lshlrev_b32_e32 v6, 16, v7
	v_and_b32_e32 v7, 0xffff0000, v7
	s_waitcnt vmcnt(0)
	v_lshlrev_b32_e32 v66, 16, v10
	v_and_b32_e32 v67, 0xffff0000, v10
	v_sqrt_f32_e32 v72, v1
	v_max_f32_e32 v1, 0, v73
	v_lshlrev_b32_e32 v10, 16, v11
	v_and_b32_e32 v11, 0xffff0000, v11
	v_pk_mul_f32 v[62:63], v[62:63], v[2:3]
	v_sqrt_f32_e32 v73, v1
	v_max_f32_e32 v1, 0, v70
	v_pk_mul_f32 v[50:51], v[72:73], v[50:51]
	v_sqrt_f32_e32 v70, v1
	v_max_f32_e32 v1, 0, v71
	v_sqrt_f32_e32 v71, v1
	s_nop 0
	v_pk_mul_f32 v[6:7], v[70:71], v[6:7]
	s_nop 0
	v_pk_mul_f32 v[6:7], v[6:7], v[10:11]
	v_pk_mul_f32 v[10:11], v[50:51], v[66:67]
	v_pk_fma_f32 v[40:41], v[40:41], v[2:3], v[6:7]
	v_lshlrev_b32_e32 v2, 16, v4
	v_and_b32_e32 v3, 0xffff0000, v4
	v_pk_mul_f32 v[2:3], v[32:33], v[2:3]
	v_lshlrev_b32_e32 v4, 16, v5
	v_mul_f32_e32 v1, 0x3fb8aa3b, v2
	v_exp_f32_e32 v2, v1
	v_mul_f32_e32 v1, 0x3fb8aa3b, v3
	v_exp_f32_e32 v3, v1
	v_and_b32_e32 v5, 0xffff0000, v5
	v_pk_mul_f32 v[4:5], v[30:31], v[4:5]
	v_pk_mul_f32 v[50:51], v[64:65], v[48:49]
	v_mul_f32_e32 v1, 0x3fb8aa3b, v4
	v_xor_b32_e32 v65, 0x80000000, v3
	v_xor_b32_e32 v64, 0x80000000, v2
	v_exp_f32_e32 v4, v1
	v_mul_f32_e32 v1, 0x3fb8aa3b, v5
	v_pk_fma_f32 v[64:65], v[64:65], v[2:3], 1.0 op_sel_hi:[1,1,0]
	v_exp_f32_e32 v5, v1
	v_max_f32_e32 v1, 0, v64
	v_pk_fma_f32 v[46:47], v[46:47], v[48:49], v[10:11]
	v_xor_b32_e32 v49, 0x80000000, v5
	v_xor_b32_e32 v48, 0x80000000, v4
	v_pk_fma_f32 v[48:49], v[48:49], v[4:5], 1.0 op_sel_hi:[1,1,0]
	v_lshlrev_b32_e32 v6, 16, v8
	v_and_b32_e32 v7, 0xffff0000, v8
	v_lshlrev_b32_e32 v8, 16, v9
	v_and_b32_e32 v9, 0xffff0000, v9
	v_lshlrev_b32_e32 v10, 16, v12
	v_sqrt_f32_e32 v64, v1
	v_max_f32_e32 v1, 0, v65
	v_and_b32_e32 v11, 0xffff0000, v12
	v_lshlrev_b32_e32 v12, 16, v13
	v_and_b32_e32 v13, 0xffff0000, v13
	v_pk_mul_f32 v[44:45], v[44:45], v[4:5]
	v_pk_mul_f32 v[42:43], v[42:43], v[2:3]
	v_sqrt_f32_e32 v65, v1
	v_max_f32_e32 v1, 0, v48
	v_pk_mul_f32 v[6:7], v[64:65], v[6:7]
	v_pk_mul_f32 v[6:7], v[6:7], v[10:11]
	v_sqrt_f32_e32 v48, v1
	v_max_f32_e32 v1, 0, v49
	v_sqrt_f32_e32 v49, v1
	s_nop 0
	v_pk_mul_f32 v[8:9], v[48:49], v[8:9]
	v_pk_fma_f32 v[48:49], v[14:15], v[2:3], v[6:7]
	v_pk_mul_f32 v[8:9], v[8:9], v[12:13]
	s_nop 0
	v_pk_fma_f32 v[8:9], v[16:17], v[4:5], v[8:9]
	global_load_dwordx4 v[4:7], v[20:21], off offset:2048
	global_load_dwordx4 v[12:15], v[36:37], off offset:2048
	s_nop 0
	global_load_dwordx4 v[36:39], v[38:39], off offset:2048
	s_waitcnt vmcnt(2)
; __device__ __forceinline__ f32x4 unpack4(u32x2 u) { return (f32x4){__uint_as_float(u.x << 16), __uint_as_float(u.x & 0xffff0000u), __uint_as_float(u.y << 16), __uint_as_float(u.y & 0xffff0000u)}; }
; template <int ph>
; __device__ __forceinline__ void run_phase(const Args& args, LAS unsigned char* lds, const int G, const int bx, const bool fin = true) {
;     ...
;             auto lru_ab = [](f32x4 gr, f32x4 gi, f32x4 xc, f32x4 sp, f32x4& a, f32x4& bb) {
;                 const f32x4 la = gr * sp; a = (f32x4){__expf(la[0]), __expf(la[1]), __expf(la[2]), __expf(la[3])};
;                 const f32x4 om = (f32x4){1.f, 1.f, 1.f, 1.f} - a * a;
;                 bb = (f32x4){sqrtf(fmaxf(om[0], 0.f)), sqrtf(fmaxf(om[1], 0.f)), sqrtf(fmaxf(om[2], 0.f)), sqrtf(fmaxf(om[3], 0.f))} * gi * xc; };
;     ...
; #pragma unroll 8
;                 for (int t = 0; t < 32; ++t) { const size_t o = base + (size_t)t * D;
;                     const u32x4 gr = *(const u32x4*)(GR + o), gi = *(const u32x4*)(GI + o), xc = *(const u32x4*)(XC + o);
;                     f32x4 a, bb;
;                     lru_ab(unpack4((u32x2){gr.x, gr.y}), unpack4((u32x2){gi.x, gi.y}), unpack4((u32x2){xc.x, xc.y}), sp0, a, bb); A0 = A0 * a; B0 = a * B0 + bb;
;                     lru_ab(unpack4((u32x2){gr.z, gr.w}), unpack4((u32x2){gi.z, gi.w}), unpack4((u32x2){xc.z, xc.w}), sp1, a, bb); A1 = A1 * a; B1 = a * B1 + bb; }
	v_lshlrev_b32_e32 v2, 16, v4
	v_and_b32_e32 v3, 0xffff0000, v4
	v_pk_mul_f32 v[2:3], v[28:29], v[2:3]
	s_waitcnt vmcnt(0)
	v_lshlrev_b32_e32 v16, 16, v36
	v_mul_f32_e32 v1, 0x3fb8aa3b, v2
	v_and_b32_e32 v17, 0xffff0000, v36
	v_exp_f32_e32 v36, v1
	v_mul_f32_e32 v1, 0x3fb8aa3b, v3
	v_lshlrev_b32_e32 v20, 16, v37
	v_and_b32_e32 v21, 0xffff0000, v37
	v_exp_f32_e32 v37, v1
	v_lshlrev_b32_e32 v4, 16, v5
	v_and_b32_e32 v5, 0xffff0000, v5
	v_pk_mul_f32 v[4:5], v[26:27], v[4:5]
	v_xor_b32_e32 v65, 0x80000000, v37
	v_mul_f32_e32 v1, 0x3fb8aa3b, v4
	v_xor_b32_e32 v64, 0x80000000, v36
	v_exp_f32_e32 v4, v1
	v_mul_f32_e32 v1, 0x3fb8aa3b, v5
	v_pk_fma_f32 v[64:65], v[64:65], v[36:37], 1.0 op_sel_hi:[1,1,0]
	v_exp_f32_e32 v5, v1
	v_max_f32_e32 v1, 0, v64
	v_xor_b32_e32 v3, 0x80000000, v5
	v_xor_b32_e32 v2, 0x80000000, v4
	v_pk_fma_f32 v[2:3], v[2:3], v[4:5], 1.0 op_sel_hi:[1,1,0]
	v_lshlrev_b32_e32 v10, 16, v12
	v_and_b32_e32 v11, 0xffff0000, v12
	v_lshlrev_b32_e32 v12, 16, v13
	v_and_b32_e32 v13, 0xffff0000, v13
	v_sqrt_f32_e32 v64, v1
	v_max_f32_e32 v1, 0, v65
	v_sqrt_f32_e32 v65, v1
	v_max_f32_e32 v1, 0, v2
	v_pk_mul_f32 v[10:11], v[64:65], v[10:11]
	v_sqrt_f32_e32 v2, v1
	v_max_f32_e32 v1, 0, v3
	v_sqrt_f32_e32 v3, v1
	s_nop 0
	v_pk_mul_f32 v[2:3], v[2:3], v[12:13]
	v_pk_mul_f32 v[12:13], v[10:11], v[16:17]
	v_pk_mul_f32 v[16:17], v[2:3], v[20:21]
	v_pk_mul_f32 v[2:3], v[62:63], v[4:5]
	v_pk_fma_f32 v[4:5], v[40:41], v[4:5], v[16:17]
	v_lshlrev_b32_e32 v16, 16, v6
	v_and_b32_e32 v17, 0xffff0000, v6
	v_pk_mul_f32 v[16:17], v[32:33], v[16:17]
	v_lshlrev_b32_e32 v6, 16, v7
	v_mul_f32_e32 v1, 0x3fb8aa3b, v16
	v_exp_f32_e32 v16, v1
	v_mul_f32_e32 v1, 0x3fb8aa3b, v17
	v_exp_f32_e32 v17, v1
	v_and_b32_e32 v7, 0xffff0000, v7
	v_pk_mul_f32 v[6:7], v[30:31], v[6:7]
	v_pk_fma_f32 v[12:13], v[46:47], v[36:37], v[12:13]
	v_mul_f32_e32 v1, 0x3fb8aa3b, v6
	v_xor_b32_e32 v47, 0x80000000, v17
	v_xor_b32_e32 v46, 0x80000000, v16
	v_exp_f32_e32 v40, v1
	v_mul_f32_e32 v1, 0x3fb8aa3b, v7
	v_pk_fma_f32 v[46:47], v[46:47], v[16:17], 1.0 op_sel_hi:[1,1,0]
	v_exp_f32_e32 v41, v1
	v_max_f32_e32 v1, 0, v46
	v_pk_mul_f32 v[10:11], v[50:51], v[36:37]
	v_xor_b32_e32 v7, 0x80000000, v41
	v_xor_b32_e32 v6, 0x80000000, v40
	v_pk_fma_f32 v[6:7], v[6:7], v[40:41], 1.0 op_sel_hi:[1,1,0]
	v_lshlrev_b32_e32 v20, 16, v14
	v_and_b32_e32 v21, 0xffff0000, v14
	v_lshlrev_b32_e32 v14, 16, v15
	v_and_b32_e32 v15, 0xffff0000, v15
	v_lshlrev_b32_e32 v36, 16, v38
	v_sqrt_f32_e32 v46, v1
	v_max_f32_e32 v1, 0, v47
	v_and_b32_e32 v37, 0xffff0000, v38
	v_lshlrev_b32_e32 v38, 16, v39
	v_and_b32_e32 v39, 0xffff0000, v39
	v_sqrt_f32_e32 v47, v1
	v_max_f32_e32 v1, 0, v6
	v_sqrt_f32_e32 v6, v1
	v_max_f32_e32 v1, 0, v7
	v_sqrt_f32_e32 v7, v1
	s_nop 0
	v_pk_mul_f32 v[6:7], v[6:7], v[14:15]
	v_pk_mul_f32 v[14:15], v[46:47], v[20:21]
	s_nop 0
	v_pk_mul_f32 v[20:21], v[14:15], v[36:37]
	v_pk_mul_f32 v[14:15], v[42:43], v[16:17]
	v_pk_fma_f32 v[16:17], v[48:49], v[16:17], v[20:21]
	v_add_co_u32_e32 v20, vcc, s55, v18
	v_pk_mul_f32 v[36:37], v[6:7], v[38:39]
	s_nop 0
	v_addc_co_u32_e32 v21, vcc, 0, v19, vcc
	v_add_co_u32_e32 v42, vcc, s62, v18
	v_pk_fma_f32 v[8:9], v[8:9], v[40:41], v[36:37]
	s_nop 0
	v_addc_co_u32_e32 v43, vcc, 0, v19, vcc
	global_load_dwordx4 v[48:51], v[42:43], off offset:-4096
	v_add_co_u32_e32 v36, vcc, s56, v18
	v_pk_mul_f32 v[6:7], v[44:45], v[40:41]
	s_nop 0
	v_addc_co_u32_e32 v37, vcc, 0, v19, vcc
	v_add_co_u32_e32 v44, vcc, s63, v18
	s_nop 1
	v_addc_co_u32_e32 v45, vcc, 0, v19, vcc
	v_add_co_u32_e32 v38, vcc, s57, v18
	global_load_dwordx4 v[62:65], v[44:45], off offset:-4096
	s_nop 0
	v_addc_co_u32_e32 v39, vcc, 0, v19, vcc
	v_add_co_u32_e32 v46, vcc, s74, v18
	s_waitcnt vmcnt(1)
	v_lshlrev_b32_e32 v18, 16, v48
	v_addc_co_u32_e32 v47, vcc, 0, v19, vcc
	global_load_dwordx4 v[70:73], v[46:47], off offset:-4096
	v_and_b32_e32 v19, 0xffff0000, v48
	v_pk_mul_f32 v[18:19], v[28:29], v[18:19]
	v_lshlrev_b32_e32 v40, 16, v49
	v_mul_f32_e32 v1, 0x3fb8aa3b, v18
	v_exp_f32_e32 v74, v1
	v_mul_f32_e32 v1, 0x3fb8aa3b, v19
	v_exp_f32_e32 v75, v1
	v_and_b32_e32 v41, 0xffff0000, v49
	v_pk_mul_f32 v[40:41], v[26:27], v[40:41]
	v_xor_b32_e32 v76, 0x80000000, v74
	v_mul_f32_e32 v1, 0x3fb8aa3b, v40
	v_xor_b32_e32 v77, 0x80000000, v75
	v_exp_f32_e32 v40, v1
	v_mul_f32_e32 v1, 0x3fb8aa3b, v41
	v_pk_fma_f32 v[76:77], v[76:77], v[74:75], 1.0 op_sel_hi:[1,1,0]
	v_exp_f32_e32 v41, v1
	v_max_f32_e32 v1, 0, v76
	v_xor_b32_e32 v19, 0x80000000, v41
	v_xor_b32_e32 v18, 0x80000000, v40
	v_pk_fma_f32 v[18:19], v[18:19], v[40:41], 1.0 op_sel_hi:[1,1,0]
	s_waitcnt vmcnt(1)
	v_lshlrev_b32_e32 v48, 16, v62
	v_and_b32_e32 v49, 0xffff0000, v62
	v_lshlrev_b32_e32 v62, 16, v63
	v_and_b32_e32 v63, 0xffff0000, v63
	v_pk_mul_f32 v[10:11], v[10:11], v[74:75]
	s_waitcnt vmcnt(0)
; __device__ __forceinline__ f32x4 unpack4(u32x2 u) { return (f32x4){__uint_as_float(u.x << 16), __uint_as_float(u.x & 0xffff0000u), __uint_as_float(u.y << 16), __uint_as_float(u.y & 0xffff0000u)}; }
; template <int ph>
; __device__ __forceinline__ void run_phase(const Args& args, LAS unsigned char* lds, const int G, const int bx, const bool fin = true) {
;     ...
;             auto lru_ab = [](f32x4 gr, f32x4 gi, f32x4 xc, f32x4 sp, f32x4& a, f32x4& bb) {
;                 const f32x4 la = gr * sp; a = (f32x4){__expf(la[0]), __expf(la[1]), __expf(la[2]), __expf(la[3])};
;                 const f32x4 om = (f32x4){1.f, 1.f, 1.f, 1.f} - a * a;
;                 bb = (f32x4){sqrtf(fmaxf(om[0], 0.f)), sqrtf(fmaxf(om[1], 0.f)), sqrtf(fmaxf(om[2], 0.f)), sqrtf(fmaxf(om[3], 0.f))} * gi * xc; };
;     ...
; #pragma unroll 8
;                 for (int t = 0; t < 32; ++t) { const size_t o = base + (size_t)t * D;
;                     const u32x4 gr = *(const u32x4*)(GR + o), gi = *(const u32x4*)(GI + o), xc = *(const u32x4*)(XC + o);
;                     f32x4 a, bb;
;                     lru_ab(unpack4((u32x2){gr.x, gr.y}), unpack4((u32x2){gi.x, gi.y}), unpack4((u32x2){xc.x, xc.y}), sp0, a, bb); A0 = A0 * a; B0 = a * B0 + bb;
;                     lru_ab(unpack4((u32x2){gr.z, gr.w}), unpack4((u32x2){gi.z, gi.w}), unpack4((u32x2){xc.z, xc.w}), sp1, a, bb); A1 = A1 * a; B1 = a * B1 + bb; }
	v_lshlrev_b32_e32 v66, 16, v70
	v_sqrt_f32_e32 v76, v1
	v_max_f32_e32 v1, 0, v77
	v_and_b32_e32 v67, 0xffff0000, v70
	v_lshlrev_b32_e32 v70, 16, v71
	v_and_b32_e32 v71, 0xffff0000, v71
	v_sqrt_f32_e32 v77, v1
	v_max_f32_e32 v1, 0, v18
	v_pk_mul_f32 v[48:49], v[76:77], v[48:49]
	v_pk_mul_f32 v[48:49], v[48:49], v[66:67]
	v_sqrt_f32_e32 v18, v1
	v_max_f32_e32 v1, 0, v19
	v_sqrt_f32_e32 v19, v1
	s_nop 0
	v_pk_mul_f32 v[18:19], v[18:19], v[62:63]
	s_nop 0
	v_pk_mul_f32 v[62:63], v[18:19], v[70:71]
	v_pk_mul_f32 v[18:19], v[2:3], v[40:41]
	v_pk_fma_f32 v[2:3], v[12:13], v[74:75], v[48:49]
	v_pk_fma_f32 v[12:13], v[4:5], v[40:41], v[62:63]
	v_lshlrev_b32_e32 v4, 16, v50
	v_and_b32_e32 v5, 0xffff0000, v50
	v_pk_mul_f32 v[4:5], v[32:33], v[4:5]
	v_lshlrev_b32_e32 v40, 16, v51
	v_mul_f32_e32 v1, 0x3fb8aa3b, v4
	v_exp_f32_e32 v66, v1
	v_mul_f32_e32 v1, 0x3fb8aa3b, v5
	v_exp_f32_e32 v67, v1
	v_and_b32_e32 v41, 0xffff0000, v51
	v_pk_mul_f32 v[40:41], v[30:31], v[40:41]
	v_xor_b32_e32 v70, 0x80000000, v66
	v_mul_f32_e32 v1, 0x3fb8aa3b, v40
	v_xor_b32_e32 v71, 0x80000000, v67
	v_exp_f32_e32 v40, v1
	v_mul_f32_e32 v1, 0x3fb8aa3b, v41
	v_pk_fma_f32 v[70:71], v[70:71], v[66:67], 1.0 op_sel_hi:[1,1,0]
	v_exp_f32_e32 v41, v1
	v_max_f32_e32 v1, 0, v70
	v_xor_b32_e32 v5, 0x80000000, v41
	v_xor_b32_e32 v4, 0x80000000, v40
	v_pk_fma_f32 v[4:5], v[4:5], v[40:41], 1.0 op_sel_hi:[1,1,0]
	v_lshlrev_b32_e32 v48, 16, v64
	v_and_b32_e32 v49, 0xffff0000, v64
	v_lshlrev_b32_e32 v50, 16, v65
	v_and_b32_e32 v51, 0xffff0000, v65
	v_lshlrev_b32_e32 v62, 16, v72
	v_and_b32_e32 v63, 0xffff0000, v72
	v_sqrt_f32_e32 v70, v1
	v_max_f32_e32 v1, 0, v71
	v_lshlrev_b32_e32 v64, 16, v73
	v_and_b32_e32 v65, 0xffff0000, v73
	v_sqrt_f32_e32 v71, v1
	v_max_f32_e32 v1, 0, v4
	v_pk_mul_f32 v[48:49], v[70:71], v[48:49]
	v_pk_mul_f32 v[48:49], v[48:49], v[62:63]
	v_sqrt_f32_e32 v4, v1
	v_max_f32_e32 v1, 0, v5
	v_sqrt_f32_e32 v5, v1
	s_nop 0
	v_pk_mul_f32 v[4:5], v[4:5], v[50:51]
	s_nop 0
	v_pk_mul_f32 v[50:51], v[4:5], v[64:65]
	v_pk_mul_f32 v[4:5], v[14:15], v[66:67]
	v_pk_mul_f32 v[14:15], v[6:7], v[40:41]
	v_pk_fma_f32 v[6:7], v[16:17], v[66:67], v[48:49]
	v_pk_fma_f32 v[8:9], v[8:9], v[40:41], v[50:51]
	global_load_dwordx4 v[48:51], v[20:21], off offset:2048
	global_load_dwordx4 v[62:65], v[36:37], off offset:2048
	s_nop 0
	global_load_dwordx4 v[36:39], v[38:39], off offset:2048
	s_waitcnt vmcnt(2)
	v_lshlrev_b32_e32 v16, 16, v48
	v_and_b32_e32 v17, 0xffff0000, v48
	v_pk_mul_f32 v[16:17], v[28:29], v[16:17]
	v_lshlrev_b32_e32 v20, 16, v49
	v_mul_f32_e32 v1, 0x3fb8aa3b, v16
	v_exp_f32_e32 v66, v1
	v_mul_f32_e32 v1, 0x3fb8aa3b, v17
	v_exp_f32_e32 v67, v1
	v_and_b32_e32 v21, 0xffff0000, v49
	v_pk_mul_f32 v[20:21], v[26:27], v[20:21]
	v_xor_b32_e32 v70, 0x80000000, v66
	v_mul_f32_e32 v1, 0x3fb8aa3b, v20
	v_xor_b32_e32 v71, 0x80000000, v67
	v_exp_f32_e32 v20, v1
	v_mul_f32_e32 v1, 0x3fb8aa3b, v21
	v_pk_fma_f32 v[70:71], v[70:71], v[66:67], 1.0 op_sel_hi:[1,1,0]
	v_exp_f32_e32 v21, v1
	v_max_f32_e32 v1, 0, v70
	v_xor_b32_e32 v17, 0x80000000, v21
	v_xor_b32_e32 v16, 0x80000000, v20
	v_pk_fma_f32 v[16:17], v[16:17], v[20:21], 1.0 op_sel_hi:[1,1,0]
	s_waitcnt vmcnt(1)
	v_lshlrev_b32_e32 v40, 16, v62
	v_and_b32_e32 v41, 0xffff0000, v62
	v_lshlrev_b32_e32 v48, 16, v63
	v_and_b32_e32 v49, 0xffff0000, v63
	s_waitcnt vmcnt(0)
	v_lshlrev_b32_e32 v62, 16, v36
	v_and_b32_e32 v63, 0xffff0000, v36
	v_sqrt_f32_e32 v70, v1
	v_max_f32_e32 v1, 0, v71
	v_lshlrev_b32_e32 v36, 16, v37
	v_and_b32_e32 v37, 0xffff0000, v37
	v_sqrt_f32_e32 v71, v1
	v_max_f32_e32 v1, 0, v16
	v_pk_mul_f32 v[40:41], v[70:71], v[40:41]
	v_pk_mul_f32 v[40:41], v[40:41], v[62:63]
	v_sqrt_f32_e32 v16, v1
	v_max_f32_e32 v1, 0, v17
	v_sqrt_f32_e32 v17, v1
	s_nop 0
	v_pk_mul_f32 v[16:17], v[16:17], v[48:49]
	v_lshlrev_b32_e32 v48, 16, v38
	v_pk_mul_f32 v[36:37], v[16:17], v[36:37]
	v_pk_mul_f32 v[16:17], v[18:19], v[20:21]
	v_pk_mul_f32 v[18:19], v[10:11], v[66:67]
	v_pk_fma_f32 v[10:11], v[12:13], v[20:21], v[36:37]
	v_pk_fma_f32 v[20:21], v[2:3], v[66:67], v[40:41]
	v_lshlrev_b32_e32 v2, 16, v50
	v_and_b32_e32 v3, 0xffff0000, v50
	v_pk_mul_f32 v[2:3], v[32:33], v[2:3]
	v_lshlrev_b32_e32 v12, 16, v51
	v_mul_f32_e32 v1, 0x3fb8aa3b, v2
	v_exp_f32_e32 v2, v1
	v_mul_f32_e32 v1, 0x3fb8aa3b, v3
	v_exp_f32_e32 v3, v1
	v_and_b32_e32 v13, 0xffff0000, v51
	v_pk_mul_f32 v[12:13], v[30:31], v[12:13]
	v_xor_b32_e32 v62, 0x80000000, v2
	v_mul_f32_e32 v1, 0x3fb8aa3b, v12
	v_xor_b32_e32 v63, 0x80000000, v3
	v_exp_f32_e32 v50, v1
	v_mul_f32_e32 v1, 0x3fb8aa3b, v13
	v_pk_fma_f32 v[62:63], v[62:63], v[2:3], 1.0 op_sel_hi:[1,1,0]
	v_exp_f32_e32 v51, v1
	v_max_f32_e32 v1, 0, v62
	v_xor_b32_e32 v13, 0x80000000, v51
	v_xor_b32_e32 v12, 0x80000000, v50
	v_pk_fma_f32 v[12:13], v[12:13], v[50:51], 1.0 op_sel_hi:[1,1,0]
	v_lshlrev_b32_e32 v36, 16, v64
	v_and_b32_e32 v37, 0xffff0000, v64
	v_lshlrev_b32_e32 v40, 16, v65
	v_and_b32_e32 v41, 0xffff0000, v65
	v_and_b32_e32 v49, 0xffff0000, v38
	v_lshlrev_b32_e32 v38, 16, v39
	v_sqrt_f32_e32 v62, v1
	v_max_f32_e32 v1, 0, v63
	v_and_b32_e32 v39, 0xffff0000, v39
	v_sqrt_f32_e32 v63, v1
	v_max_f32_e32 v1, 0, v12
	v_pk_mul_f32 v[36:37], v[62:63], v[36:37]
	v_pk_mul_f32 v[36:37], v[36:37], v[48:49]
	v_pk_fma_f32 v[36:37], v[6:7], v[2:3], v[36:37]
	v_sqrt_f32_e32 v12, v1
	v_max_f32_e32 v1, 0, v13
	v_sqrt_f32_e32 v13, v1
	s_nop 0
	v_pk_mul_f32 v[12:13], v[12:13], v[40:41]
	s_nop 0
	v_pk_mul_f32 v[38:39], v[12:13], v[38:39]
	v_pk_mul_f32 v[12:13], v[14:15], v[50:51]
	v_pk_mul_f32 v[14:15], v[4:5], v[2:3]
	v_pk_fma_f32 v[8:9], v[8:9], v[50:51], v[38:39]
	global_load_dwordx4 v[2:5], v[42:43], off
	global_load_dwordx4 v[38:41], v[44:45], off
	global_load_dwordx4 v[62:65], v[46:47], off
	s_waitcnt vmcnt(2)
; __device__ __forceinline__ f32x4 unpack4(u32x2 u) { return (f32x4){__uint_as_float(u.x << 16), __uint_as_float(u.x & 0xffff0000u), __uint_as_float(u.y << 16), __uint_as_float(u.y & 0xffff0000u)}; }
; template <int ph>
; __device__ __forceinline__ void run_phase(const Args& args, LAS unsigned char* lds, const int G, const int bx, const bool fin = true) {
;     ...
;             auto lru_ab = [](f32x4 gr, f32x4 gi, f32x4 xc, f32x4 sp, f32x4& a, f32x4& bb) {
;                 const f32x4 la = gr * sp; a = (f32x4){__expf(la[0]), __expf(la[1]), __expf(la[2]), __expf(la[3])};
;                 const f32x4 om = (f32x4){1.f, 1.f, 1.f, 1.f} - a * a;
;                 bb = (f32x4){sqrtf(fmaxf(om[0], 0.f)), sqrtf(fmaxf(om[1], 0.f)), sqrtf(fmaxf(om[2], 0.f)), sqrtf(fmaxf(om[3], 0.f))} * gi * xc; };
;     ...
; #pragma unroll 8
;                 for (int t = 0; t < 32; ++t) { const size_t o = base + (size_t)t * D;
;                     const u32x4 gr = *(const u32x4*)(GR + o), gi = *(const u32x4*)(GI + o), xc = *(const u32x4*)(XC + o);
;                     f32x4 a, bb;
;                     lru_ab(unpack4((u32x2){gr.x, gr.y}), unpack4((u32x2){gi.x, gi.y}), unpack4((u32x2){xc.x, xc.y}), sp0, a, bb); A0 = A0 * a; B0 = a * B0 + bb;
;                     lru_ab(unpack4((u32x2){gr.z, gr.w}), unpack4((u32x2){gi.z, gi.w}), unpack4((u32x2){xc.z, xc.w}), sp1, a, bb); A1 = A1 * a; B1 = a * B1 + bb; }
	v_lshlrev_b32_e32 v6, 16, v2
	v_and_b32_e32 v7, 0xffff0000, v2
	v_pk_mul_f32 v[6:7], v[28:29], v[6:7]
	v_lshlrev_b32_e32 v2, 16, v3
	v_mul_f32_e32 v1, 0x3fb8aa3b, v6
	v_exp_f32_e32 v66, v1
	v_mul_f32_e32 v1, 0x3fb8aa3b, v7
	v_exp_f32_e32 v67, v1
	v_and_b32_e32 v3, 0xffff0000, v3
	v_pk_mul_f32 v[2:3], v[26:27], v[2:3]
	v_xor_b32_e32 v6, 0x80000000, v66
	v_mul_f32_e32 v1, 0x3fb8aa3b, v2
	v_xor_b32_e32 v7, 0x80000000, v67
	v_exp_f32_e32 v70, v1
	v_mul_f32_e32 v1, 0x3fb8aa3b, v3
	v_pk_fma_f32 v[6:7], v[6:7], v[66:67], 1.0 op_sel_hi:[1,1,0]
	v_exp_f32_e32 v71, v1
	v_max_f32_e32 v1, 0, v6
	v_xor_b32_e32 v3, 0x80000000, v71
	v_xor_b32_e32 v2, 0x80000000, v70
	v_pk_fma_f32 v[2:3], v[2:3], v[70:71], 1.0 op_sel_hi:[1,1,0]
	s_waitcnt vmcnt(1)
	v_lshlrev_b32_e32 v48, 16, v38
	v_and_b32_e32 v49, 0xffff0000, v38
	v_lshlrev_b32_e32 v38, 16, v39
	v_and_b32_e32 v39, 0xffff0000, v39
	s_waitcnt vmcnt(0)
	v_lshlrev_b32_e32 v50, 16, v62
	v_and_b32_e32 v51, 0xffff0000, v62
	v_sqrt_f32_e32 v6, v1
	v_max_f32_e32 v1, 0, v7
	v_lshlrev_b32_e32 v62, 16, v63
	v_and_b32_e32 v63, 0xffff0000, v63
	v_sqrt_f32_e32 v7, v1
	v_max_f32_e32 v1, 0, v2
	v_pk_mul_f32 v[6:7], v[6:7], v[48:49]
	v_pk_mul_f32 v[48:49], v[6:7], v[50:51]
	v_pk_mul_f32 v[6:7], v[16:17], v[70:71]
	v_lshlrev_b32_e32 v16, 16, v40
	v_and_b32_e32 v17, 0xffff0000, v40
	v_pk_fma_f32 v[48:49], v[20:21], v[66:67], v[48:49]
	v_lshlrev_b32_e32 v20, 16, v64
	v_and_b32_e32 v21, 0xffff0000, v64
	s_nop 0
	v_sqrt_f32_e32 v2, v1
	v_max_f32_e32 v1, 0, v3
	v_sqrt_f32_e32 v3, v1
	s_nop 0
	v_pk_mul_f32 v[2:3], v[2:3], v[38:39]
	s_nop 0
	v_pk_mul_f32 v[38:39], v[2:3], v[62:63]
	v_pk_mul_f32 v[2:3], v[18:19], v[66:67]
	v_pk_fma_f32 v[50:51], v[10:11], v[70:71], v[38:39]
	v_lshlrev_b32_e32 v10, 16, v4
	v_and_b32_e32 v11, 0xffff0000, v4
	v_pk_mul_f32 v[10:11], v[32:33], v[10:11]
	v_lshlrev_b32_e32 v4, 16, v5
	v_mul_f32_e32 v1, 0x3fb8aa3b, v10
	v_exp_f32_e32 v10, v1
	v_mul_f32_e32 v1, 0x3fb8aa3b, v11
	v_exp_f32_e32 v11, v1
	v_and_b32_e32 v5, 0xffff0000, v5
	v_pk_mul_f32 v[4:5], v[30:31], v[4:5]
	v_xor_b32_e32 v62, 0x80000000, v10
	v_mul_f32_e32 v1, 0x3fb8aa3b, v4
	v_xor_b32_e32 v63, 0x80000000, v11
	v_exp_f32_e32 v4, v1
	v_mul_f32_e32 v1, 0x3fb8aa3b, v5
	v_pk_fma_f32 v[62:63], v[62:63], v[10:11], 1.0 op_sel_hi:[1,1,0]
	v_exp_f32_e32 v5, v1
	v_max_f32_e32 v1, 0, v62
	v_lshlrev_b32_e32 v18, 16, v41
	v_and_b32_e32 v19, 0xffff0000, v41
	v_xor_b32_e32 v41, 0x80000000, v5
	v_xor_b32_e32 v40, 0x80000000, v4
	v_pk_fma_f32 v[40:41], v[40:41], v[4:5], 1.0 op_sel_hi:[1,1,0]
	v_lshlrev_b32_e32 v38, 16, v65
	v_and_b32_e32 v39, 0xffff0000, v65
	v_sqrt_f32_e32 v62, v1
	v_max_f32_e32 v1, 0, v63
	v_sqrt_f32_e32 v63, v1
	v_max_f32_e32 v1, 0, v40
	v_pk_mul_f32 v[16:17], v[62:63], v[16:17]
	v_pk_mul_f32 v[16:17], v[16:17], v[20:21]
	v_pk_mul_f32 v[20:21], v[14:15], v[10:11]
	v_pk_fma_f32 v[36:37], v[36:37], v[10:11], v[16:17]
	v_sqrt_f32_e32 v40, v1
	v_max_f32_e32 v1, 0, v41
	v_sqrt_f32_e32 v41, v1
	s_nop 0
	v_pk_mul_f32 v[18:19], v[40:41], v[18:19]
	s_nop 0
	v_pk_mul_f32 v[18:19], v[18:19], v[38:39]
	v_pk_mul_f32 v[38:39], v[12:13], v[4:5]
	v_pk_fma_f32 v[40:41], v[8:9], v[4:5], v[18:19]
	global_load_dwordx4 v[16:19], v[42:43], off offset:2048
	global_load_dwordx4 v[12:15], v[44:45], off offset:2048
	global_load_dwordx4 v[8:11], v[46:47], off offset:2048
	s_waitcnt vmcnt(2)
	v_lshlrev_b32_e32 v4, 16, v16
	v_and_b32_e32 v5, 0xffff0000, v16
	v_pk_mul_f32 v[4:5], v[28:29], v[4:5]
	v_lshlrev_b32_e32 v16, 16, v17
	v_mul_f32_e32 v1, 0x3fb8aa3b, v4
	v_exp_f32_e32 v46, v1
	v_mul_f32_e32 v1, 0x3fb8aa3b, v5
	v_exp_f32_e32 v47, v1
	v_and_b32_e32 v17, 0xffff0000, v17
	v_pk_mul_f32 v[16:17], v[26:27], v[16:17]
	v_xor_b32_e32 v62, 0x80000000, v46
	v_mul_f32_e32 v1, 0x3fb8aa3b, v16
	v_xor_b32_e32 v63, 0x80000000, v47
	v_exp_f32_e32 v4, v1
	v_mul_f32_e32 v1, 0x3fb8aa3b, v17
	v_pk_fma_f32 v[62:63], v[62:63], v[46:47], 1.0 op_sel_hi:[1,1,0]
	v_exp_f32_e32 v5, v1
	v_max_f32_e32 v1, 0, v62
	v_xor_b32_e32 v17, 0x80000000, v5
	v_xor_b32_e32 v16, 0x80000000, v4
	v_pk_fma_f32 v[16:17], v[16:17], v[4:5], 1.0 op_sel_hi:[1,1,0]
	s_waitcnt vmcnt(1)
	v_lshlrev_b32_e32 v42, 16, v12
	v_and_b32_e32 v43, 0xffff0000, v12
	v_lshlrev_b32_e32 v12, 16, v13
	v_and_b32_e32 v13, 0xffff0000, v13
	s_waitcnt vmcnt(0)
	v_lshlrev_b32_e32 v44, 16, v8
	v_and_b32_e32 v45, 0xffff0000, v8
	v_sqrt_f32_e32 v62, v1
	v_max_f32_e32 v1, 0, v63
	v_lshlrev_b32_e32 v8, 16, v9
	v_and_b32_e32 v9, 0xffff0000, v9
	v_sqrt_f32_e32 v63, v1
	v_max_f32_e32 v1, 0, v16
	v_sqrt_f32_e32 v16, v1
	v_max_f32_e32 v1, 0, v17
	v_sqrt_f32_e32 v17, v1
	s_nop 0
	v_pk_mul_f32 v[12:13], v[16:17], v[12:13]
	v_pk_mul_f32 v[16:17], v[62:63], v[42:43]
	v_pk_mul_f32 v[12:13], v[12:13], v[8:9]
	v_pk_mul_f32 v[16:17], v[16:17], v[44:45]
	v_pk_mul_f32 v[8:9], v[6:7], v[4:5]
	v_pk_mul_f32 v[6:7], v[2:3], v[46:47]
	v_pk_fma_f32 v[2:3], v[48:49], v[46:47], v[16:17]
	v_lshlrev_b32_e32 v16, 16, v18
	v_and_b32_e32 v17, 0xffff0000, v18
	v_pk_fma_f32 v[4:5], v[50:51], v[4:5], v[12:13]
	v_lshlrev_b32_e32 v12, 16, v14
	v_and_b32_e32 v13, 0xffff0000, v14
	v_lshlrev_b32_e32 v42, 16, v15
	v_and_b32_e32 v43, 0xffff0000, v15
	v_pk_mul_f32 v[14:15], v[32:33], v[16:17]
	v_lshlrev_b32_e32 v44, 16, v19
	v_mul_f32_e32 v1, 0x3fb8aa3b, v14
	v_exp_f32_e32 v14, v1
	v_mul_f32_e32 v1, 0x3fb8aa3b, v15
	v_exp_f32_e32 v15, v1
	v_and_b32_e32 v45, 0xffff0000, v19
	v_pk_mul_f32 v[44:45], v[30:31], v[44:45]
	v_xor_b32_e32 v46, 0x80000000, v14
	v_mul_f32_e32 v1, 0x3fb8aa3b, v44
	v_xor_b32_e32 v47, 0x80000000, v15
	v_exp_f32_e32 v16, v1
	v_mul_f32_e32 v1, 0x3fb8aa3b, v45
	v_pk_fma_f32 v[46:47], v[46:47], v[14:15], 1.0 op_sel_hi:[1,1,0]
	v_exp_f32_e32 v17, v1
	v_max_f32_e32 v1, 0, v46
	v_xor_b32_e32 v45, 0x80000000, v17
	v_xor_b32_e32 v44, 0x80000000, v16
	v_pk_fma_f32 v[44:45], v[44:45], v[16:17], 1.0 op_sel_hi:[1,1,0]
	v_lshlrev_b32_e32 v18, 16, v10
	v_and_b32_e32 v19, 0xffff0000, v10
	v_lshlrev_b32_e32 v10, 16, v11
	v_and_b32_e32 v11, 0xffff0000, v11
	v_sqrt_f32_e32 v46, v1
	v_max_f32_e32 v1, 0, v47
	v_sqrt_f32_e32 v47, v1
	v_max_f32_e32 v1, 0, v44
	v_pk_mul_f32 v[12:13], v[46:47], v[12:13]
	v_pk_mul_f32 v[18:19], v[12:13], v[18:19]
	v_pk_mul_f32 v[12:13], v[38:39], v[16:17]
	v_sqrt_f32_e32 v44, v1
	v_max_f32_e32 v1, 0, v45
	v_sqrt_f32_e32 v45, v1
	s_nop 0
	v_pk_mul_f32 v[42:43], v[44:45], v[42:43]
	s_nop 0
	v_pk_mul_f32 v[42:43], v[42:43], v[10:11]
	v_pk_mul_f32 v[10:11], v[20:21], v[14:15]
	v_pk_fma_f32 v[16:17], v[40:41], v[16:17], v[42:43]
	v_pk_fma_f32 v[14:15], v[36:37], v[14:15], v[18:19]
	s_cbranch_scc0 .LBB0_1061
; template <int ph>
; __device__ __forceinline__ void run_phase(const Args& args, LAS unsigned char* lds, const int G, const int bx, const bool fin = true) {
;     ...
;                 sA[(seg * 8 + l8) * 2] = A0; sA[(seg * 8 + l8) * 2 + 1] = A1; sB[(seg * 8 + l8) * 2] = B0; sB[(seg * 8 + l8) * 2 + 1] = B1;
;                 __syncthreads();
;                 f32x4 h0 = (f32x4){0.f, 0.f, 0.f, 0.f}, h1 = h0;
;                 for (int s2 = 0; s2 < seg; ++s2) { h0 = sA[(s2 * 8 + l8) * 2] * h0 + sB[(s2 * 8 + l8) * 2]; h1 = sA[(s2 * 8 + l8) * 2 + 1] * h1 + sB[(s2 * 8 + l8) * 2 + 1]; }
	ds_write_b128 v53, v[6:9]
	ds_write_b128 v53, v[10:13] offset:16
	ds_write_b128 v53, v[2:5] offset:16384
	ds_write_b128 v53, v[14:17] offset:16400
	v_mov_b32_e32 v9, 0
	v_mov_b32_e32 v8, 0
	v_mov_b32_e32 v7, 0
	v_mov_b32_e32 v6, 0
	v_mov_b32_e32 v5, 0
	v_mov_b32_e32 v4, 0
	v_mov_b32_e32 v3, 0
	v_mov_b32_e32 v2, 0
	s_waitcnt lgkmcnt(0)
	s_barrier
	s_and_saveexec_b64 s[0:1], s[2:3]
	s_cbranch_execz .LBB0_1072
	v_mov_b32_e32 v2, v0
	v_mov_b32_e32 v3, v0
	v_mov_b32_e32 v1, v0
	v_mov_b64_e32 v[8:9], v[2:3]
	v_mov_b64_e32 v[6:7], v[0:1]
	v_mov_b64_e32 v[4:5], v[2:3]
	v_mov_b32_e32 v10, 0
	v_mov_b64_e32 v[2:3], v[0:1]
	s_and_saveexec_b64 s[24:25], s[6:7]
	s_cbranch_execz .LBB0_1067
	v_mov_b32_e32 v2, 0
	s_mov_b32 s10, 0
	s_mov_b64 s[26:27], 0
	v_mov_b32_e32 v1, v56
	v_mov_b32_e32 v3, v2
	v_mov_b32_e32 v4, v2
	v_mov_b32_e32 v5, v2
	v_mov_b32_e32 v6, v2
	v_mov_b32_e32 v7, v2
	v_mov_b32_e32 v8, v2
	v_mov_b32_e32 v9, v2

; __device__ __forceinline__ f32x4 unpack4(u32x2 u) { return (f32x4){__uint_as_float(u.x << 16), __uint_as_float(u.x & 0xffff0000u), __uint_as_float(u.y << 16), __uint_as_float(u.y & 0xffff0000u)}; }
; __device__ __forceinline__ u32x2 pack4(f32x4 v) { u32x2 r; r.x = cvt_pk_bf16(v.x, v.y); r.y = cvt_pk_bf16(v.z, v.w); return r; }
; template <int ph>
; __device__ __forceinline__ void run_phase(const Args& args, LAS unsigned char* lds, const int G, const int bx, const bool fin = true) {
;     ...
;             auto lru_ab = [](f32x4 gr, f32x4 gi, f32x4 xc, f32x4 sp, f32x4& a, f32x4& bb) {
;                 const f32x4 la = gr * sp; a = (f32x4){__expf(la[0]), __expf(la[1]), __expf(la[2]), __expf(la[3])};
;                 const f32x4 om = (f32x4){1.f, 1.f, 1.f, 1.f} - a * a;
;                 bb = (f32x4){sqrtf(fmaxf(om[0], 0.f)), sqrtf(fmaxf(om[1], 0.f)), sqrtf(fmaxf(om[2], 0.f)), sqrtf(fmaxf(om[3], 0.f))} * gi * xc; };
;     ...
; #pragma unroll 8
;                 for (int t = 0; t < 32; ++t) { const size_t o = base + (size_t)t * D;
;                     const u32x4 gr = *(const u32x4*)(GR + o), gi = *(const u32x4*)(GI + o), xc = *(const u32x4*)(XC + o), gg = *(const u32x4*)(GG + o);
;                     f32x4 a, bb;
;                     lru_ab(unpack4((u32x2){gr.x, gr.y}), unpack4((u32x2){gi.x, gi.y}), unpack4((u32x2){xc.x, xc.y}), sp0, a, bb); h0 = a * h0 + bb;
;                     lru_ab(unpack4((u32x2){gr.z, gr.w}), unpack4((u32x2){gi.z, gi.w}), unpack4((u32x2){xc.z, xc.w}), sp1, a, bb); h1 = a * h1 + bb;
;                     const u32x2 w0 = pack4(h0 * unpack4((u32x2){gg.x, gg.y})), w1 = pack4(h1 * unpack4((u32x2){gg.z, gg.w}));
;                     *(u32x4*)(LO + o) = (u32x4){w0.x, w0.y, w1.x, w1.y}; }
.LBB0_1073:
	s_nop 0
	v_lshl_add_u64 v[10:11], v[34:35], 0, s[24:25]
	v_add_co_u32_e32 v44, vcc, 0x10700000, v10
	s_add_u32 s24, s24, 0x4000
	s_nop 0
	v_addc_co_u32_e32 v45, vcc, 0, v11, vcc
	global_load_dwordx4 v[14:17], v[44:45], off
	v_add_co_u32_e32 v12, vcc, 0x16a00000, v10
	s_addc_u32 s25, s25, 0
	s_nop 0
	v_addc_co_u32_e32 v13, vcc, 0, v11, vcc
	v_add_co_u32_e32 v46, vcc, 0x7d80000, v10
	global_load_dwordx4 v[18:21], v[12:13], off
	s_nop 0
	v_addc_co_u32_e32 v47, vcc, 0, v11, vcc
	global_load_dwordx4 v[36:39], v[46:47], off
	v_add_co_u32_e32 v48, vcc, 0x12800000, v10
	s_cmp_eq_u32 s24, 0x10000
	s_nop 0
	v_addc_co_u32_e32 v49, vcc, 0, v11, vcc
	global_load_dwordx4 v[40:43], v[48:49], off
	s_waitcnt vmcnt(3)
	v_lshlrev_b32_e32 v50, 16, v14
	v_and_b32_e32 v51, 0xffff0000, v14
	v_pk_mul_f32 v[50:51], v[28:29], v[50:51]
	v_lshlrev_b32_e32 v14, 16, v15
	v_mul_f32_e32 v1, 0x3fb8aa3b, v50
	v_exp_f32_e32 v50, v1
	v_mul_f32_e32 v1, 0x3fb8aa3b, v51
	v_exp_f32_e32 v51, v1
	v_and_b32_e32 v15, 0xffff0000, v15
	v_pk_mul_f32 v[14:15], v[26:27], v[14:15]
	v_xor_b32_e32 v70, 0x80000000, v50
	v_mul_f32_e32 v1, 0x3fb8aa3b, v14
	v_xor_b32_e32 v71, 0x80000000, v51
	v_exp_f32_e32 v14, v1
	v_mul_f32_e32 v1, 0x3fb8aa3b, v15
	v_pk_fma_f32 v[70:71], v[70:71], v[50:51], 1.0 op_sel_hi:[1,1,0]
	v_exp_f32_e32 v15, v1
	v_max_f32_e32 v1, 0, v70
	v_xor_b32_e32 v67, 0x80000000, v15
	v_xor_b32_e32 v66, 0x80000000, v14
	v_pk_fma_f32 v[66:67], v[66:67], v[14:15], 1.0 op_sel_hi:[1,1,0]
	s_waitcnt vmcnt(2)
	v_lshlrev_b32_e32 v62, 16, v18
	v_and_b32_e32 v63, 0xffff0000, v18
	v_lshlrev_b32_e32 v18, 16, v19
	v_and_b32_e32 v19, 0xffff0000, v19
	s_waitcnt vmcnt(1)
	v_lshlrev_b32_e32 v64, 16, v36
	v_and_b32_e32 v65, 0xffff0000, v36
	v_sqrt_f32_e32 v70, v1
	v_max_f32_e32 v1, 0, v71
	v_lshlrev_b32_e32 v36, 16, v37
	v_and_b32_e32 v37, 0xffff0000, v37
	v_sqrt_f32_e32 v71, v1
	v_max_f32_e32 v1, 0, v66
	v_pk_mul_f32 v[62:63], v[70:71], v[62:63]
	v_sqrt_f32_e32 v66, v1
	v_max_f32_e32 v1, 0, v67
	v_sqrt_f32_e32 v67, v1
	s_nop 0
	v_pk_mul_f32 v[18:19], v[66:67], v[18:19]
	s_nop 0
	v_pk_mul_f32 v[18:19], v[18:19], v[36:37]
	v_pk_mul_f32 v[36:37], v[62:63], v[64:65]
	v_pk_fma_f32 v[62:63], v[4:5], v[14:15], v[18:19]
	v_pk_fma_f32 v[50:51], v[2:3], v[50:51], v[36:37]
	v_lshlrev_b32_e32 v2, 16, v16
	v_and_b32_e32 v3, 0xffff0000, v16
	v_pk_mul_f32 v[2:3], v[32:33], v[2:3]
	v_lshlrev_b32_e32 v4, 16, v17
	v_mul_f32_e32 v1, 0x3fb8aa3b, v2
	v_exp_f32_e32 v2, v1
	v_mul_f32_e32 v1, 0x3fb8aa3b, v3
	v_exp_f32_e32 v3, v1
	v_and_b32_e32 v5, 0xffff0000, v17
	v_pk_mul_f32 v[4:5], v[30:31], v[4:5]
	v_lshlrev_b32_e32 v14, 16, v20
	v_and_b32_e32 v15, 0xffff0000, v20
	v_lshlrev_b32_e32 v16, 16, v21
	v_and_b32_e32 v17, 0xffff0000, v21
	v_lshlrev_b32_e32 v18, 16, v38
	v_and_b32_e32 v19, 0xffff0000, v38
	v_lshlrev_b32_e32 v20, 16, v39
	v_and_b32_e32 v21, 0xffff0000, v39
	v_mul_f32_e32 v1, 0x3fb8aa3b, v4
	v_xor_b32_e32 v39, 0x80000000, v3
	v_xor_b32_e32 v38, 0x80000000, v2
	v_exp_f32_e32 v4, v1
	v_mul_f32_e32 v1, 0x3fb8aa3b, v5
	v_pk_fma_f32 v[38:39], v[38:39], v[2:3], 1.0 op_sel_hi:[1,1,0]
	v_exp_f32_e32 v5, v1
	v_max_f32_e32 v1, 0, v38
	v_xor_b32_e32 v37, 0x80000000, v5
	v_xor_b32_e32 v36, 0x80000000, v4
	v_pk_fma_f32 v[36:37], v[36:37], v[4:5], 1.0 op_sel_hi:[1,1,0]
	v_sqrt_f32_e32 v38, v1
	v_max_f32_e32 v1, 0, v39
	v_sqrt_f32_e32 v39, v1
	v_max_f32_e32 v1, 0, v36
	v_pk_mul_f32 v[14:15], v[38:39], v[14:15]
	v_pk_mul_f32 v[14:15], v[14:15], v[18:19]
	v_pk_fma_f32 v[64:65], v[6:7], v[2:3], v[14:15]
	s_waitcnt vmcnt(0)
	v_lshlrev_b32_e32 v2, 16, v40
	v_and_b32_e32 v3, 0xffff0000, v40
	v_pk_mul_f32 v[2:3], v[50:51], v[2:3]
	v_lshlrev_b32_e32 v6, 16, v43
	v_sqrt_f32_e32 v36, v1
	v_max_f32_e32 v1, 0, v37
	v_cvt_pk_bf16_f32 v2, v2, v3
	v_and_b32_e32 v7, 0xffff0000, v43
	v_sqrt_f32_e32 v37, v1
	s_nop 0
	v_pk_mul_f32 v[16:17], v[36:37], v[16:17]
	s_nop 0
	v_pk_mul_f32 v[16:17], v[16:17], v[20:21]
	s_nop 0
	v_pk_fma_f32 v[8:9], v[8:9], v[4:5], v[16:17]
	v_lshlrev_b32_e32 v4, 16, v41
	v_and_b32_e32 v5, 0xffff0000, v41
	v_pk_mul_f32 v[4:5], v[62:63], v[4:5]
	v_pk_mul_f32 v[6:7], v[8:9], v[6:7]
	v_cvt_pk_bf16_f32 v3, v4, v5
	v_lshlrev_b32_e32 v4, 16, v42
	v_and_b32_e32 v5, 0xffff0000, v42
	v_pk_mul_f32 v[4:5], v[64:65], v[4:5]
	s_nop 0
	v_cvt_pk_bf16_f32 v4, v4, v5
	v_cvt_pk_bf16_f32 v5, v6, v7
	global_store_dwordx4 v[12:13], v[2:5], off
	global_load_dwordx4 v[4:7], v[44:45], off offset:2048
	s_nop 0
	global_load_dwordx4 v[14:17], v[12:13], off offset:2048
	global_load_dwordx4 v[18:21], v[46:47], off offset:2048
	global_load_dwordx4 v[36:39], v[48:49], off offset:2048
	s_waitcnt vmcnt(3)
	v_lshlrev_b32_e32 v2, 16, v4
	v_and_b32_e32 v3, 0xffff0000, v4
	v_pk_mul_f32 v[2:3], v[28:29], v[2:3]
	v_lshlrev_b32_e32 v4, 16, v5
	v_mul_f32_e32 v1, 0x3fb8aa3b, v2
	v_exp_f32_e32 v2, v1
	v_mul_f32_e32 v1, 0x3fb8aa3b, v3
	v_exp_f32_e32 v3, v1
	v_and_b32_e32 v5, 0xffff0000, v5
	v_pk_mul_f32 v[4:5], v[26:27], v[4:5]
	v_xor_b32_e32 v46, 0x80000000, v2
	v_mul_f32_e32 v1, 0x3fb8aa3b, v4
	v_xor_b32_e32 v47, 0x80000000, v3
	v_exp_f32_e32 v4, v1
	v_mul_f32_e32 v1, 0x3fb8aa3b, v5
	v_pk_fma_f32 v[46:47], v[46:47], v[2:3], 1.0 op_sel_hi:[1,1,0]
	v_exp_f32_e32 v5, v1
	v_max_f32_e32 v1, 0, v46
	v_xor_b32_e32 v45, 0x80000000, v5
	v_xor_b32_e32 v44, 0x80000000, v4
	v_pk_fma_f32 v[44:45], v[44:45], v[4:5], 1.0 op_sel_hi:[1,1,0]
	s_waitcnt vmcnt(2)
	v_lshlrev_b32_e32 v40, 16, v14
	v_and_b32_e32 v41, 0xffff0000, v14
	v_lshlrev_b32_e32 v14, 16, v15
	v_and_b32_e32 v15, 0xffff0000, v15
	s_waitcnt vmcnt(1)
; __device__ __forceinline__ f32x4 unpack4(u32x2 u) { return (f32x4){__uint_as_float(u.x << 16), __uint_as_float(u.x & 0xffff0000u), __uint_as_float(u.y << 16), __uint_as_float(u.y & 0xffff0000u)}; }
; __device__ __forceinline__ u32x2 pack4(f32x4 v) { u32x2 r; r.x = cvt_pk_bf16(v.x, v.y); r.y = cvt_pk_bf16(v.z, v.w); return r; }
; template <int ph>
; __device__ __forceinline__ void run_phase(const Args& args, LAS unsigned char* lds, const int G, const int bx, const bool fin = true) {
;     ...
;             auto lru_ab = [](f32x4 gr, f32x4 gi, f32x4 xc, f32x4 sp, f32x4& a, f32x4& bb) {
;                 const f32x4 la = gr * sp; a = (f32x4){__expf(la[0]), __expf(la[1]), __expf(la[2]), __expf(la[3])};
;                 const f32x4 om = (f32x4){1.f, 1.f, 1.f, 1.f} - a * a;
;                 bb = (f32x4){sqrtf(fmaxf(om[0], 0.f)), sqrtf(fmaxf(om[1], 0.f)), sqrtf(fmaxf(om[2], 0.f)), sqrtf(fmaxf(om[3], 0.f))} * gi * xc; };
;     ...
; #pragma unroll 8
;                 for (int t = 0; t < 32; ++t) { const size_t o = base + (size_t)t * D;
;                     const u32x4 gr = *(const u32x4*)(GR + o), gi = *(const u32x4*)(GI + o), xc = *(const u32x4*)(XC + o), gg = *(const u32x4*)(GG + o);
;                     f32x4 a, bb;
;                     lru_ab(unpack4((u32x2){gr.x, gr.y}), unpack4((u32x2){gi.x, gi.y}), unpack4((u32x2){xc.x, xc.y}), sp0, a, bb); h0 = a * h0 + bb;
;                     lru_ab(unpack4((u32x2){gr.z, gr.w}), unpack4((u32x2){gi.z, gi.w}), unpack4((u32x2){xc.z, xc.w}), sp1, a, bb); h1 = a * h1 + bb;
;                     const u32x2 w0 = pack4(h0 * unpack4((u32x2){gg.x, gg.y})), w1 = pack4(h1 * unpack4((u32x2){gg.z, gg.w}));
;                     *(u32x4*)(LO + o) = (u32x4){w0.x, w0.y, w1.x, w1.y}; }
	v_lshlrev_b32_e32 v42, 16, v18
	v_and_b32_e32 v43, 0xffff0000, v18
	v_sqrt_f32_e32 v46, v1
	v_max_f32_e32 v1, 0, v47
	v_lshlrev_b32_e32 v18, 16, v19
	v_and_b32_e32 v19, 0xffff0000, v19
	v_sqrt_f32_e32 v47, v1
	v_max_f32_e32 v1, 0, v44
	v_pk_mul_f32 v[40:41], v[46:47], v[40:41]
	v_sqrt_f32_e32 v44, v1
	v_max_f32_e32 v1, 0, v45
	v_sqrt_f32_e32 v45, v1
	s_nop 0
	v_pk_mul_f32 v[14:15], v[44:45], v[14:15]
	s_nop 0
	v_pk_mul_f32 v[14:15], v[14:15], v[18:19]
	v_pk_mul_f32 v[18:19], v[40:41], v[42:43]
	v_pk_fma_f32 v[4:5], v[62:63], v[4:5], v[14:15]
	v_lshlrev_b32_e32 v14, 16, v6
	v_and_b32_e32 v15, 0xffff0000, v6
	v_pk_mul_f32 v[14:15], v[32:33], v[14:15]
	v_lshlrev_b32_e32 v6, 16, v7
	v_mul_f32_e32 v1, 0x3fb8aa3b, v14
	v_exp_f32_e32 v14, v1
	v_mul_f32_e32 v1, 0x3fb8aa3b, v15
	v_exp_f32_e32 v15, v1
	v_and_b32_e32 v7, 0xffff0000, v7
	v_pk_mul_f32 v[6:7], v[30:31], v[6:7]
	v_xor_b32_e32 v44, 0x80000000, v14
	v_mul_f32_e32 v1, 0x3fb8aa3b, v6
	v_xor_b32_e32 v45, 0x80000000, v15
	v_exp_f32_e32 v42, v1
	v_mul_f32_e32 v1, 0x3fb8aa3b, v7
	v_pk_fma_f32 v[44:45], v[44:45], v[14:15], 1.0 op_sel_hi:[1,1,0]
	v_exp_f32_e32 v43, v1
	v_max_f32_e32 v1, 0, v44
	v_xor_b32_e32 v7, 0x80000000, v43
	v_xor_b32_e32 v6, 0x80000000, v42
	v_pk_fma_f32 v[6:7], v[6:7], v[42:43], 1.0 op_sel_hi:[1,1,0]
	v_pk_fma_f32 v[2:3], v[50:51], v[2:3], v[18:19]
	v_lshlrev_b32_e32 v18, 16, v16
	v_and_b32_e32 v19, 0xffff0000, v16
	v_lshlrev_b32_e32 v16, 16, v17
	v_and_b32_e32 v17, 0xffff0000, v17
	v_lshlrev_b32_e32 v40, 16, v20
	v_sqrt_f32_e32 v44, v1
	v_max_f32_e32 v1, 0, v45
	v_and_b32_e32 v41, 0xffff0000, v20
	v_lshlrev_b32_e32 v20, 16, v21
	v_and_b32_e32 v21, 0xffff0000, v21
	v_sqrt_f32_e32 v45, v1
	v_max_f32_e32 v1, 0, v6
	v_pk_mul_f32 v[18:19], v[44:45], v[18:19]
	v_sqrt_f32_e32 v6, v1
	v_max_f32_e32 v1, 0, v7
	v_sqrt_f32_e32 v7, v1
	s_nop 0
	v_pk_mul_f32 v[6:7], v[6:7], v[16:17]
	s_nop 0
	v_pk_mul_f32 v[16:17], v[6:7], v[20:21]
	v_pk_mul_f32 v[6:7], v[18:19], v[40:41]
	v_pk_fma_f32 v[8:9], v[8:9], v[42:43], v[16:17]
	v_pk_fma_f32 v[6:7], v[64:65], v[14:15], v[6:7]
	s_waitcnt vmcnt(0)
	v_lshlrev_b32_e32 v14, 16, v36
	v_and_b32_e32 v15, 0xffff0000, v36
	v_lshlrev_b32_e32 v16, 16, v37
	v_and_b32_e32 v17, 0xffff0000, v37
	v_pk_mul_f32 v[16:17], v[4:5], v[16:17]
	v_pk_mul_f32 v[14:15], v[2:3], v[14:15]
	v_lshlrev_b32_e32 v18, 16, v39
	v_cvt_pk_bf16_f32 v14, v14, v15
	v_cvt_pk_bf16_f32 v15, v16, v17
	v_lshlrev_b32_e32 v16, 16, v38
	v_and_b32_e32 v17, 0xffff0000, v38
	v_and_b32_e32 v19, 0xffff0000, v39
	v_pk_mul_f32 v[18:19], v[8:9], v[18:19]
	v_pk_mul_f32 v[16:17], v[6:7], v[16:17]
	v_add_co_u32_e32 v36, vcc, s52, v10
	v_cvt_pk_bf16_f32 v16, v16, v17
	v_cvt_pk_bf16_f32 v17, v18, v19
	v_addc_co_u32_e32 v37, vcc, 0, v11, vcc
	global_store_dwordx4 v[12:13], v[14:17], off offset:2048
	s_nop 1
	v_add_co_u32_e32 v14, vcc, s55, v10
	s_nop 1
	v_addc_co_u32_e32 v15, vcc, 0, v11, vcc
	global_load_dwordx4 v[38:41], v[14:15], off offset:-4096
	v_add_co_u32_e32 v20, vcc, s53, v10
	s_nop 1
	v_addc_co_u32_e32 v21, vcc, 0, v11, vcc
	v_add_co_u32_e32 v12, vcc, s56, v10
	s_nop 1
	v_addc_co_u32_e32 v13, vcc, 0, v11, vcc
	v_add_co_u32_e32 v50, vcc, s54, v10
	global_load_dwordx4 v[42:45], v[12:13], off offset:-4096
	s_nop 0
	v_addc_co_u32_e32 v51, vcc, 0, v11, vcc
	v_add_co_u32_e32 v16, vcc, s57, v10
	s_waitcnt vmcnt(1)
	v_lshlrev_b32_e32 v70, 16, v38
	v_addc_co_u32_e32 v17, vcc, 0, v11, vcc
	global_load_dwordx4 v[46:49], v[16:17], off offset:-4096
	v_and_b32_e32 v71, 0xffff0000, v38
	v_pk_mul_f32 v[70:71], v[28:29], v[70:71]
	v_lshlrev_b32_e32 v38, 16, v39
	v_mul_f32_e32 v1, 0x3fb8aa3b, v70
	v_exp_f32_e32 v70, v1
	v_mul_f32_e32 v1, 0x3fb8aa3b, v71
	v_exp_f32_e32 v71, v1
	v_and_b32_e32 v39, 0xffff0000, v39
	v_add_co_u32_e32 v66, vcc, s75, v10
	v_pk_mul_f32 v[38:39], v[26:27], v[38:39]
	s_nop 0
	v_addc_co_u32_e32 v67, vcc, 0, v11, vcc
	v_mul_f32_e32 v1, 0x3fb8aa3b, v38
	v_xor_b32_e32 v79, 0x80000000, v71
	v_xor_b32_e32 v78, 0x80000000, v70
	v_add_co_u32_e32 v18, vcc, s76, v10
	v_exp_f32_e32 v38, v1
	v_mul_f32_e32 v1, 0x3fb8aa3b, v39
	v_pk_fma_f32 v[78:79], v[78:79], v[70:71], 1.0 op_sel_hi:[1,1,0]
	v_addc_co_u32_e32 v19, vcc, 0, v11, vcc
	v_exp_f32_e32 v39, v1
	v_max_f32_e32 v1, 0, v78
	v_xor_b32_e32 v77, 0x80000000, v39
	v_xor_b32_e32 v76, 0x80000000, v38
	v_pk_fma_f32 v[76:77], v[76:77], v[38:39], 1.0 op_sel_hi:[1,1,0]
	global_load_dwordx4 v[62:65], v[18:19], off offset:-4096
	s_waitcnt vmcnt(2)
	v_lshlrev_b32_e32 v72, 16, v42
	v_and_b32_e32 v73, 0xffff0000, v42
	v_lshlrev_b32_e32 v42, 16, v43
	v_and_b32_e32 v43, 0xffff0000, v43
	s_waitcnt vmcnt(1)
	v_lshlrev_b32_e32 v74, 16, v46
	v_sqrt_f32_e32 v78, v1
	v_max_f32_e32 v1, 0, v79
	v_and_b32_e32 v75, 0xffff0000, v46
	v_lshlrev_b32_e32 v46, 16, v47
	v_and_b32_e32 v47, 0xffff0000, v47
	v_sqrt_f32_e32 v79, v1
	v_max_f32_e32 v1, 0, v76
	v_pk_mul_f32 v[72:73], v[78:79], v[72:73]
	v_sqrt_f32_e32 v76, v1
	v_max_f32_e32 v1, 0, v77
	v_sqrt_f32_e32 v77, v1
	s_nop 0
	v_pk_mul_f32 v[42:43], v[76:77], v[42:43]
	s_nop 0
	v_pk_mul_f32 v[42:43], v[42:43], v[46:47]
	v_pk_mul_f32 v[46:47], v[72:73], v[74:75]
	s_nop 0
	v_pk_fma_f32 v[46:47], v[2:3], v[70:71], v[46:47]
	v_lshlrev_b32_e32 v2, 16, v40
	v_and_b32_e32 v3, 0xffff0000, v40
	v_pk_mul_f32 v[2:3], v[32:33], v[2:3]
	v_pk_fma_f32 v[70:71], v[4:5], v[38:39], v[42:43]
	v_mul_f32_e32 v1, 0x3fb8aa3b, v2
	v_exp_f32_e32 v2, v1
	v_mul_f32_e32 v1, 0x3fb8aa3b, v3
	v_exp_f32_e32 v3, v1
	v_lshlrev_b32_e32 v4, 16, v41
	v_and_b32_e32 v5, 0xffff0000, v41
	v_pk_mul_f32 v[4:5], v[30:31], v[4:5]
	v_xor_b32_e32 v73, 0x80000000, v3
	v_mul_f32_e32 v1, 0x3fb8aa3b, v4
	v_xor_b32_e32 v72, 0x80000000, v2
	v_exp_f32_e32 v4, v1
	v_mul_f32_e32 v1, 0x3fb8aa3b, v5
	v_pk_fma_f32 v[72:73], v[72:73], v[2:3], 1.0 op_sel_hi:[1,1,0]
	v_exp_f32_e32 v5, v1
	v_max_f32_e32 v1, 0, v72
	v_lshlrev_b32_e32 v38, 16, v44
	v_and_b32_e32 v39, 0xffff0000, v44
	v_lshlrev_b32_e32 v40, 16, v45
	v_and_b32_e32 v41, 0xffff0000, v45
	v_lshlrev_b32_e32 v42, 16, v48
	v_and_b32_e32 v43, 0xffff0000, v48
	v_lshlrev_b32_e32 v44, 16, v49
	v_and_b32_e32 v45, 0xffff0000, v49
	v_xor_b32_e32 v49, 0x80000000, v5
	v_sqrt_f32_e32 v72, v1
	v_max_f32_e32 v1, 0, v73
	v_xor_b32_e32 v48, 0x80000000, v4
	v_pk_fma_f32 v[48:49], v[48:49], v[4:5], 1.0 op_sel_hi:[1,1,0]
	v_sqrt_f32_e32 v73, v1
	v_max_f32_e32 v1, 0, v48
	v_pk_mul_f32 v[38:39], v[72:73], v[38:39]
	v_pk_mul_f32 v[38:39], v[38:39], v[42:43]
	v_sqrt_f32_e32 v48, v1
	v_max_f32_e32 v1, 0, v49
	v_sqrt_f32_e32 v49, v1
	s_nop 0
	v_pk_mul_f32 v[40:41], v[48:49], v[40:41]
	s_nop 0
	v_pk_mul_f32 v[40:41], v[40:41], v[44:45]
	v_pk_fma_f32 v[44:45], v[6:7], v[2:3], v[38:39]
	v_pk_fma_f32 v[48:49], v[8:9], v[4:5], v[40:41]
	s_waitcnt vmcnt(0)
; __device__ __forceinline__ f32x4 unpack4(u32x2 u) { return (f32x4){__uint_as_float(u.x << 16), __uint_as_float(u.x & 0xffff0000u), __uint_as_float(u.y << 16), __uint_as_float(u.y & 0xffff0000u)}; }
; __device__ __forceinline__ u32x2 pack4(f32x4 v) { u32x2 r; r.x = cvt_pk_bf16(v.x, v.y); r.y = cvt_pk_bf16(v.z, v.w); return r; }
; template <int ph>
; __device__ __forceinline__ void run_phase(const Args& args, LAS unsigned char* lds, const int G, const int bx, const bool fin = true) {
;     ...
;             auto lru_ab = [](f32x4 gr, f32x4 gi, f32x4 xc, f32x4 sp, f32x4& a, f32x4& bb) {
;                 const f32x4 la = gr * sp; a = (f32x4){__expf(la[0]), __expf(la[1]), __expf(la[2]), __expf(la[3])};
;                 const f32x4 om = (f32x4){1.f, 1.f, 1.f, 1.f} - a * a;
;                 bb = (f32x4){sqrtf(fmaxf(om[0], 0.f)), sqrtf(fmaxf(om[1], 0.f)), sqrtf(fmaxf(om[2], 0.f)), sqrtf(fmaxf(om[3], 0.f))} * gi * xc; };
;     ...
; #pragma unroll 8
;                 for (int t = 0; t < 32; ++t) { const size_t o = base + (size_t)t * D;
;                     const u32x4 gr = *(const u32x4*)(GR + o), gi = *(const u32x4*)(GI + o), xc = *(const u32x4*)(XC + o), gg = *(const u32x4*)(GG + o);
;                     f32x4 a, bb;
;                     lru_ab(unpack4((u32x2){gr.x, gr.y}), unpack4((u32x2){gi.x, gi.y}), unpack4((u32x2){xc.x, xc.y}), sp0, a, bb); h0 = a * h0 + bb;
;                     lru_ab(unpack4((u32x2){gr.z, gr.w}), unpack4((u32x2){gi.z, gi.w}), unpack4((u32x2){xc.z, xc.w}), sp1, a, bb); h1 = a * h1 + bb;
;                     const u32x2 w0 = pack4(h0 * unpack4((u32x2){gg.x, gg.y})), w1 = pack4(h1 * unpack4((u32x2){gg.z, gg.w}));
;                     *(u32x4*)(LO + o) = (u32x4){w0.x, w0.y, w1.x, w1.y}; }
	v_lshlrev_b32_e32 v2, 16, v62
	v_and_b32_e32 v3, 0xffff0000, v62
	v_lshlrev_b32_e32 v4, 16, v63
	v_and_b32_e32 v5, 0xffff0000, v63
	v_pk_mul_f32 v[4:5], v[70:71], v[4:5]
	v_pk_mul_f32 v[2:3], v[46:47], v[2:3]
	v_lshlrev_b32_e32 v6, 16, v65
	v_cvt_pk_bf16_f32 v2, v2, v3
	v_cvt_pk_bf16_f32 v3, v4, v5
	v_lshlrev_b32_e32 v4, 16, v64
	v_and_b32_e32 v5, 0xffff0000, v64
	v_and_b32_e32 v7, 0xffff0000, v65
	v_pk_mul_f32 v[6:7], v[48:49], v[6:7]
	v_pk_mul_f32 v[4:5], v[44:45], v[4:5]
	s_nop 0
	v_cvt_pk_bf16_f32 v4, v4, v5
	v_cvt_pk_bf16_f32 v5, v6, v7
	global_store_dwordx4 v[12:13], v[2:5], off offset:-4096
	global_load_dwordx4 v[2:5], v[36:37], off offset:2048
	s_nop 0
	global_load_dwordx4 v[6:9], v[20:21], off offset:2048
	global_load_dwordx4 v[36:39], v[50:51], off offset:2048
	global_load_dwordx4 v[40:43], v[66:67], off offset:2048
	s_waitcnt vmcnt(3)
	v_lshlrev_b32_e32 v50, 16, v2
	v_and_b32_e32 v51, 0xffff0000, v2
	v_pk_mul_f32 v[50:51], v[28:29], v[50:51]
	v_lshlrev_b32_e32 v2, 16, v3
	v_mul_f32_e32 v1, 0x3fb8aa3b, v50
	v_exp_f32_e32 v50, v1
	v_mul_f32_e32 v1, 0x3fb8aa3b, v51
	v_exp_f32_e32 v51, v1
	v_and_b32_e32 v3, 0xffff0000, v3
	v_pk_mul_f32 v[2:3], v[26:27], v[2:3]
	v_xor_b32_e32 v72, 0x80000000, v50
	v_mul_f32_e32 v1, 0x3fb8aa3b, v2
	v_xor_b32_e32 v73, 0x80000000, v51
	v_exp_f32_e32 v2, v1
	v_mul_f32_e32 v1, 0x3fb8aa3b, v3
	v_pk_fma_f32 v[72:73], v[72:73], v[50:51], 1.0 op_sel_hi:[1,1,0]
	v_exp_f32_e32 v3, v1
	v_max_f32_e32 v1, 0, v72
	v_xor_b32_e32 v67, 0x80000000, v3
	v_xor_b32_e32 v66, 0x80000000, v2
	v_pk_fma_f32 v[66:67], v[66:67], v[2:3], 1.0 op_sel_hi:[1,1,0]
	s_waitcnt vmcnt(2)
	v_lshlrev_b32_e32 v62, 16, v6
	v_and_b32_e32 v63, 0xffff0000, v6
	v_lshlrev_b32_e32 v6, 16, v7
	v_and_b32_e32 v7, 0xffff0000, v7
	s_waitcnt vmcnt(1)
	v_lshlrev_b32_e32 v64, 16, v36
	v_and_b32_e32 v65, 0xffff0000, v36
	v_sqrt_f32_e32 v72, v1
	v_max_f32_e32 v1, 0, v73
	v_lshlrev_b32_e32 v36, 16, v37
	v_and_b32_e32 v37, 0xffff0000, v37
	v_sqrt_f32_e32 v73, v1
	v_max_f32_e32 v1, 0, v66
	v_pk_mul_f32 v[62:63], v[72:73], v[62:63]
	v_sqrt_f32_e32 v66, v1
	v_max_f32_e32 v1, 0, v67
	v_sqrt_f32_e32 v67, v1
	s_nop 0
	v_pk_mul_f32 v[6:7], v[66:67], v[6:7]
	s_nop 0
	v_pk_mul_f32 v[6:7], v[6:7], v[36:37]
	v_pk_mul_f32 v[36:37], v[62:63], v[64:65]
	s_nop 0
	v_pk_fma_f32 v[46:47], v[46:47], v[50:51], v[36:37]
	v_pk_fma_f32 v[50:51], v[70:71], v[2:3], v[6:7]
	v_lshlrev_b32_e32 v2, 16, v4
	v_and_b32_e32 v3, 0xffff0000, v4
	v_pk_mul_f32 v[2:3], v[32:33], v[2:3]
	v_lshlrev_b32_e32 v4, 16, v5
	v_mul_f32_e32 v1, 0x3fb8aa3b, v2
	v_exp_f32_e32 v2, v1
	v_mul_f32_e32 v1, 0x3fb8aa3b, v3
	v_exp_f32_e32 v3, v1
	v_and_b32_e32 v5, 0xffff0000, v5
	v_pk_mul_f32 v[4:5], v[30:31], v[4:5]
	v_xor_b32_e32 v64, 0x80000000, v2
	v_mul_f32_e32 v1, 0x3fb8aa3b, v4
	v_xor_b32_e32 v65, 0x80000000, v3
	v_exp_f32_e32 v4, v1
	v_mul_f32_e32 v1, 0x3fb8aa3b, v5
	v_pk_fma_f32 v[64:65], v[64:65], v[2:3], 1.0 op_sel_hi:[1,1,0]
	v_exp_f32_e32 v5, v1
	v_max_f32_e32 v1, 0, v64
	v_xor_b32_e32 v63, 0x80000000, v5
	v_xor_b32_e32 v62, 0x80000000, v4
	v_pk_fma_f32 v[62:63], v[62:63], v[4:5], 1.0 op_sel_hi:[1,1,0]
	v_lshlrev_b32_e32 v6, 16, v8
	v_and_b32_e32 v7, 0xffff0000, v8
	v_lshlrev_b32_e32 v8, 16, v9
	v_and_b32_e32 v9, 0xffff0000, v9
	v_lshlrev_b32_e32 v36, 16, v38
	v_and_b32_e32 v37, 0xffff0000, v38
	v_sqrt_f32_e32 v64, v1
	v_max_f32_e32 v1, 0, v65
	v_lshlrev_b32_e32 v38, 16, v39
	v_and_b32_e32 v39, 0xffff0000, v39
	v_sqrt_f32_e32 v65, v1
	v_max_f32_e32 v1, 0, v62
	v_pk_mul_f32 v[6:7], v[64:65], v[6:7]
	v_pk_mul_f32 v[6:7], v[6:7], v[36:37]
	v_pk_fma_f32 v[44:45], v[44:45], v[2:3], v[6:7]
	s_waitcnt vmcnt(0)
	v_lshlrev_b32_e32 v2, 16, v40
	v_and_b32_e32 v3, 0xffff0000, v40
	v_pk_mul_f32 v[2:3], v[46:47], v[2:3]
	v_lshlrev_b32_e32 v6, 16, v43
	v_sqrt_f32_e32 v62, v1
	v_max_f32_e32 v1, 0, v63
	v_cvt_pk_bf16_f32 v2, v2, v3
	v_and_b32_e32 v7, 0xffff0000, v43
	v_sqrt_f32_e32 v63, v1
	s_nop 0
	v_pk_mul_f32 v[8:9], v[62:63], v[8:9]
	s_nop 0
	v_pk_mul_f32 v[8:9], v[8:9], v[38:39]
	s_nop 0
	v_pk_fma_f32 v[48:49], v[48:49], v[4:5], v[8:9]
	v_lshlrev_b32_e32 v4, 16, v41
	v_and_b32_e32 v5, 0xffff0000, v41
	v_pk_mul_f32 v[4:5], v[50:51], v[4:5]
	v_pk_mul_f32 v[6:7], v[48:49], v[6:7]
	v_cvt_pk_bf16_f32 v3, v4, v5
	v_lshlrev_b32_e32 v4, 16, v42
	v_and_b32_e32 v5, 0xffff0000, v42
	v_pk_mul_f32 v[4:5], v[44:45], v[4:5]
	s_nop 0
	v_cvt_pk_bf16_f32 v4, v4, v5
	v_cvt_pk_bf16_f32 v5, v6, v7
	global_store_dwordx4 v[20:21], v[2:5], off offset:2048
	global_load_dwordx4 v[2:5], v[14:15], off
	s_nop 0
	global_load_dwordx4 v[6:9], v[12:13], off
	global_load_dwordx4 v[36:39], v[16:17], off
	global_load_dwordx4 v[40:43], v[18:19], off
	s_waitcnt vmcnt(3)
	v_lshlrev_b32_e32 v20, 16, v2
	v_and_b32_e32 v21, 0xffff0000, v2
	v_pk_mul_f32 v[20:21], v[28:29], v[20:21]
	v_lshlrev_b32_e32 v2, 16, v3
	v_mul_f32_e32 v1, 0x3fb8aa3b, v20
	v_exp_f32_e32 v20, v1
	v_mul_f32_e32 v1, 0x3fb8aa3b, v21
	v_exp_f32_e32 v21, v1
	v_and_b32_e32 v3, 0xffff0000, v3
	v_pk_mul_f32 v[2:3], v[26:27], v[2:3]
	v_xor_b32_e32 v70, 0x80000000, v20
	v_mul_f32_e32 v1, 0x3fb8aa3b, v2
	v_xor_b32_e32 v71, 0x80000000, v21
	v_exp_f32_e32 v2, v1
	v_mul_f32_e32 v1, 0x3fb8aa3b, v3
	v_pk_fma_f32 v[70:71], v[70:71], v[20:21], 1.0 op_sel_hi:[1,1,0]
	v_exp_f32_e32 v3, v1
	v_max_f32_e32 v1, 0, v70
	v_xor_b32_e32 v67, 0x80000000, v3
	v_xor_b32_e32 v66, 0x80000000, v2
	v_pk_fma_f32 v[66:67], v[66:67], v[2:3], 1.0 op_sel_hi:[1,1,0]
	s_waitcnt vmcnt(2)
	v_lshlrev_b32_e32 v62, 16, v6
	v_and_b32_e32 v63, 0xffff0000, v6
	v_lshlrev_b32_e32 v6, 16, v7
	v_and_b32_e32 v7, 0xffff0000, v7
	s_waitcnt vmcnt(1)
; __device__ __forceinline__ f32x4 unpack4(u32x2 u) { return (f32x4){__uint_as_float(u.x << 16), __uint_as_float(u.x & 0xffff0000u), __uint_as_float(u.y << 16), __uint_as_float(u.y & 0xffff0000u)}; }
; __device__ __forceinline__ u32x2 pack4(f32x4 v) { u32x2 r; r.x = cvt_pk_bf16(v.x, v.y); r.y = cvt_pk_bf16(v.z, v.w); return r; }
; template <int ph>
; __device__ __forceinline__ void run_phase(const Args& args, LAS unsigned char* lds, const int G, const int bx, const bool fin = true) {
;     ...
;             auto lru_ab = [](f32x4 gr, f32x4 gi, f32x4 xc, f32x4 sp, f32x4& a, f32x4& bb) {
;                 const f32x4 la = gr * sp; a = (f32x4){__expf(la[0]), __expf(la[1]), __expf(la[2]), __expf(la[3])};
;                 const f32x4 om = (f32x4){1.f, 1.f, 1.f, 1.f} - a * a;
;                 bb = (f32x4){sqrtf(fmaxf(om[0], 0.f)), sqrtf(fmaxf(om[1], 0.f)), sqrtf(fmaxf(om[2], 0.f)), sqrtf(fmaxf(om[3], 0.f))} * gi * xc; };
;     ...
; #pragma unroll 8
;                 for (int t = 0; t < 32; ++t) { const size_t o = base + (size_t)t * D;
;                     const u32x4 gr = *(const u32x4*)(GR + o), gi = *(const u32x4*)(GI + o), xc = *(const u32x4*)(XC + o), gg = *(const u32x4*)(GG + o);
;                     f32x4 a, bb;
;                     lru_ab(unpack4((u32x2){gr.x, gr.y}), unpack4((u32x2){gi.x, gi.y}), unpack4((u32x2){xc.x, xc.y}), sp0, a, bb); h0 = a * h0 + bb;
;                     lru_ab(unpack4((u32x2){gr.z, gr.w}), unpack4((u32x2){gi.z, gi.w}), unpack4((u32x2){xc.z, xc.w}), sp1, a, bb); h1 = a * h1 + bb;
;                     const u32x2 w0 = pack4(h0 * unpack4((u32x2){gg.x, gg.y})), w1 = pack4(h1 * unpack4((u32x2){gg.z, gg.w}));
;                     *(u32x4*)(LO + o) = (u32x4){w0.x, w0.y, w1.x, w1.y}; }
	v_lshlrev_b32_e32 v64, 16, v36
	v_and_b32_e32 v65, 0xffff0000, v36
	v_sqrt_f32_e32 v70, v1
	v_max_f32_e32 v1, 0, v71
	v_lshlrev_b32_e32 v36, 16, v37
	v_and_b32_e32 v37, 0xffff0000, v37
	v_sqrt_f32_e32 v71, v1
	v_max_f32_e32 v1, 0, v66
	v_pk_mul_f32 v[62:63], v[70:71], v[62:63]
	v_sqrt_f32_e32 v66, v1
	v_max_f32_e32 v1, 0, v67
	v_sqrt_f32_e32 v67, v1
	s_nop 0
	v_pk_mul_f32 v[6:7], v[66:67], v[6:7]
	s_nop 0
	v_pk_mul_f32 v[6:7], v[6:7], v[36:37]
	v_pk_mul_f32 v[36:37], v[62:63], v[64:65]
	v_pk_fma_f32 v[50:51], v[50:51], v[2:3], v[6:7]
	v_lshlrev_b32_e32 v2, 16, v4
	v_and_b32_e32 v3, 0xffff0000, v4
	v_pk_mul_f32 v[2:3], v[32:33], v[2:3]
	v_lshlrev_b32_e32 v4, 16, v5
	v_mul_f32_e32 v1, 0x3fb8aa3b, v2
	v_exp_f32_e32 v2, v1
	v_mul_f32_e32 v1, 0x3fb8aa3b, v3
	v_exp_f32_e32 v3, v1
	v_and_b32_e32 v5, 0xffff0000, v5
	v_pk_mul_f32 v[4:5], v[30:31], v[4:5]
	v_xor_b32_e32 v62, 0x80000000, v2
	v_mul_f32_e32 v1, 0x3fb8aa3b, v4
	v_xor_b32_e32 v63, 0x80000000, v3
	v_exp_f32_e32 v4, v1
	v_mul_f32_e32 v1, 0x3fb8aa3b, v5
	v_pk_fma_f32 v[62:63], v[62:63], v[2:3], 1.0 op_sel_hi:[1,1,0]
	v_exp_f32_e32 v5, v1
	v_max_f32_e32 v1, 0, v62
	v_pk_fma_f32 v[46:47], v[46:47], v[20:21], v[36:37]
	v_lshlrev_b32_e32 v20, 16, v38
	v_and_b32_e32 v21, 0xffff0000, v38
	v_lshlrev_b32_e32 v36, 16, v39
	v_and_b32_e32 v37, 0xffff0000, v39
	v_xor_b32_e32 v39, 0x80000000, v5
	v_xor_b32_e32 v38, 0x80000000, v4
	v_pk_fma_f32 v[38:39], v[38:39], v[4:5], 1.0 op_sel_hi:[1,1,0]
	v_lshlrev_b32_e32 v6, 16, v8
	v_sqrt_f32_e32 v62, v1
	v_max_f32_e32 v1, 0, v63
	v_and_b32_e32 v7, 0xffff0000, v8
	v_lshlrev_b32_e32 v8, 16, v9
	v_and_b32_e32 v9, 0xffff0000, v9
	v_sqrt_f32_e32 v63, v1
	v_max_f32_e32 v1, 0, v38
	v_pk_mul_f32 v[6:7], v[62:63], v[6:7]
	v_pk_mul_f32 v[6:7], v[6:7], v[20:21]
	v_pk_fma_f32 v[44:45], v[44:45], v[2:3], v[6:7]
	s_waitcnt vmcnt(0)
	v_lshlrev_b32_e32 v2, 16, v40
	v_and_b32_e32 v3, 0xffff0000, v40
	v_pk_mul_f32 v[2:3], v[46:47], v[2:3]
	v_lshlrev_b32_e32 v6, 16, v43
	v_sqrt_f32_e32 v38, v1
	v_max_f32_e32 v1, 0, v39
	v_cvt_pk_bf16_f32 v2, v2, v3
	v_and_b32_e32 v7, 0xffff0000, v43
	v_sqrt_f32_e32 v39, v1
	s_nop 0
	v_pk_mul_f32 v[8:9], v[38:39], v[8:9]
	s_nop 0
	v_pk_mul_f32 v[8:9], v[8:9], v[36:37]
	s_nop 0
	v_pk_fma_f32 v[8:9], v[48:49], v[4:5], v[8:9]
	v_lshlrev_b32_e32 v4, 16, v41
	v_and_b32_e32 v5, 0xffff0000, v41
	v_pk_mul_f32 v[4:5], v[50:51], v[4:5]
	v_pk_mul_f32 v[6:7], v[8:9], v[6:7]
	v_cvt_pk_bf16_f32 v3, v4, v5
	v_lshlrev_b32_e32 v4, 16, v42
	v_and_b32_e32 v5, 0xffff0000, v42
	v_pk_mul_f32 v[4:5], v[44:45], v[4:5]
	s_nop 0
	v_cvt_pk_bf16_f32 v4, v4, v5
	v_cvt_pk_bf16_f32 v5, v6, v7
	global_store_dwordx4 v[12:13], v[2:5], off
	global_load_dwordx4 v[4:7], v[14:15], off offset:2048
	s_nop 0
	global_load_dwordx4 v[36:39], v[12:13], off offset:2048
	s_nop 0
	global_load_dwordx4 v[14:17], v[16:17], off offset:2048
	s_nop 0
	global_load_dwordx4 v[18:21], v[18:19], off offset:2048
	s_waitcnt vmcnt(3)
	v_lshlrev_b32_e32 v2, 16, v4
	v_and_b32_e32 v3, 0xffff0000, v4
	v_pk_mul_f32 v[2:3], v[28:29], v[2:3]
	v_lshlrev_b32_e32 v4, 16, v5
	v_mul_f32_e32 v1, 0x3fb8aa3b, v2
	v_exp_f32_e32 v2, v1
	v_mul_f32_e32 v1, 0x3fb8aa3b, v3
	v_exp_f32_e32 v3, v1
	v_and_b32_e32 v5, 0xffff0000, v5
	v_pk_mul_f32 v[4:5], v[26:27], v[4:5]
	v_xor_b32_e32 v62, 0x80000000, v2
	v_mul_f32_e32 v1, 0x3fb8aa3b, v4
	v_xor_b32_e32 v63, 0x80000000, v3
	v_exp_f32_e32 v4, v1
	v_mul_f32_e32 v1, 0x3fb8aa3b, v5
	v_pk_fma_f32 v[62:63], v[62:63], v[2:3], 1.0 op_sel_hi:[1,1,0]
	v_exp_f32_e32 v5, v1
	v_max_f32_e32 v1, 0, v62
	v_xor_b32_e32 v49, 0x80000000, v5
	v_xor_b32_e32 v48, 0x80000000, v4
	v_pk_fma_f32 v[48:49], v[48:49], v[4:5], 1.0 op_sel_hi:[1,1,0]
	s_waitcnt vmcnt(2)
	v_lshlrev_b32_e32 v40, 16, v36
	v_and_b32_e32 v41, 0xffff0000, v36
	v_lshlrev_b32_e32 v36, 16, v37
	v_and_b32_e32 v37, 0xffff0000, v37
	s_waitcnt vmcnt(1)
	v_lshlrev_b32_e32 v42, 16, v14
	v_and_b32_e32 v43, 0xffff0000, v14
	v_sqrt_f32_e32 v62, v1
	v_max_f32_e32 v1, 0, v63
	v_lshlrev_b32_e32 v14, 16, v15
	v_and_b32_e32 v15, 0xffff0000, v15
	v_sqrt_f32_e32 v63, v1
	v_max_f32_e32 v1, 0, v48
	v_pk_mul_f32 v[40:41], v[62:63], v[40:41]
	v_sqrt_f32_e32 v48, v1
	v_max_f32_e32 v1, 0, v49
	v_sqrt_f32_e32 v49, v1
	s_nop 0
	v_pk_mul_f32 v[36:37], v[48:49], v[36:37]
	s_nop 0
	v_pk_mul_f32 v[14:15], v[36:37], v[14:15]
	v_pk_mul_f32 v[36:37], v[40:41], v[42:43]
	v_pk_fma_f32 v[4:5], v[50:51], v[4:5], v[14:15]
	v_lshlrev_b32_e32 v14, 16, v6
	v_and_b32_e32 v15, 0xffff0000, v6
	v_pk_mul_f32 v[14:15], v[32:33], v[14:15]
	v_lshlrev_b32_e32 v6, 16, v7
	v_mul_f32_e32 v1, 0x3fb8aa3b, v14
	v_exp_f32_e32 v14, v1
	v_mul_f32_e32 v1, 0x3fb8aa3b, v15
	v_exp_f32_e32 v15, v1
	v_and_b32_e32 v7, 0xffff0000, v7
	v_pk_mul_f32 v[6:7], v[30:31], v[6:7]
	v_pk_fma_f32 v[2:3], v[46:47], v[2:3], v[36:37]
	v_mul_f32_e32 v1, 0x3fb8aa3b, v6
	v_xor_b32_e32 v47, 0x80000000, v15
	v_xor_b32_e32 v46, 0x80000000, v14
	v_exp_f32_e32 v42, v1
	v_mul_f32_e32 v1, 0x3fb8aa3b, v7
	v_pk_fma_f32 v[46:47], v[46:47], v[14:15], 1.0 op_sel_hi:[1,1,0]
	v_exp_f32_e32 v43, v1
	v_max_f32_e32 v1, 0, v46
	v_xor_b32_e32 v7, 0x80000000, v43
	v_xor_b32_e32 v6, 0x80000000, v42
	v_pk_fma_f32 v[6:7], v[6:7], v[42:43], 1.0 op_sel_hi:[1,1,0]
	v_lshlrev_b32_e32 v36, 16, v38
	v_and_b32_e32 v37, 0xffff0000, v38
	v_lshlrev_b32_e32 v38, 16, v39
	v_and_b32_e32 v39, 0xffff0000, v39
	v_lshlrev_b32_e32 v40, 16, v16
	v_and_b32_e32 v41, 0xffff0000, v16
	v_sqrt_f32_e32 v46, v1
	v_max_f32_e32 v1, 0, v47
	v_lshlrev_b32_e32 v16, 16, v17
	v_and_b32_e32 v17, 0xffff0000, v17
	v_sqrt_f32_e32 v47, v1
	v_max_f32_e32 v1, 0, v6
	v_pk_mul_f32 v[36:37], v[46:47], v[36:37]
	v_sqrt_f32_e32 v6, v1
	v_max_f32_e32 v1, 0, v7
	v_sqrt_f32_e32 v7, v1
	s_nop 0
	v_pk_mul_f32 v[6:7], v[6:7], v[38:39]
	s_nop 0
	v_pk_mul_f32 v[16:17], v[6:7], v[16:17]
	v_pk_mul_f32 v[6:7], v[36:37], v[40:41]
	v_pk_fma_f32 v[8:9], v[8:9], v[42:43], v[16:17]
	v_pk_fma_f32 v[6:7], v[44:45], v[14:15], v[6:7]
	s_waitcnt vmcnt(0)
; __device__ __forceinline__ f32x4 unpack4(u32x2 u) { return (f32x4){__uint_as_float(u.x << 16), __uint_as_float(u.x & 0xffff0000u), __uint_as_float(u.y << 16), __uint_as_float(u.y & 0xffff0000u)}; }
; __device__ __forceinline__ u32x2 pack4(f32x4 v) { u32x2 r; r.x = cvt_pk_bf16(v.x, v.y); r.y = cvt_pk_bf16(v.z, v.w); return r; }
; template <int ph>
; __device__ __forceinline__ void run_phase(const Args& args, LAS unsigned char* lds, const int G, const int bx, const bool fin = true) {
;     ...
;             auto lru_ab = [](f32x4 gr, f32x4 gi, f32x4 xc, f32x4 sp, f32x4& a, f32x4& bb) {
;                 const f32x4 la = gr * sp; a = (f32x4){__expf(la[0]), __expf(la[1]), __expf(la[2]), __expf(la[3])};
;                 const f32x4 om = (f32x4){1.f, 1.f, 1.f, 1.f} - a * a;
;                 bb = (f32x4){sqrtf(fmaxf(om[0], 0.f)), sqrtf(fmaxf(om[1], 0.f)), sqrtf(fmaxf(om[2], 0.f)), sqrtf(fmaxf(om[3], 0.f))} * gi * xc; };
;     ...
;                 for (int t = 0; t < 32; ++t) { const size_t o = base + (size_t)t * D;
;                     const u32x4 gr = *(const u32x4*)(GR + o), gi = *(const u32x4*)(GI + o), xc = *(const u32x4*)(XC + o), gg = *(const u32x4*)(GG + o);
;                     f32x4 a, bb;
;                     lru_ab(unpack4((u32x2){gr.x, gr.y}), unpack4((u32x2){gi.x, gi.y}), unpack4((u32x2){xc.x, xc.y}), sp0, a, bb); h0 = a * h0 + bb;
;                     lru_ab(unpack4((u32x2){gr.z, gr.w}), unpack4((u32x2){gi.z, gi.w}), unpack4((u32x2){xc.z, xc.w}), sp1, a, bb); h1 = a * h1 + bb;
;                     const u32x2 w0 = pack4(h0 * unpack4((u32x2){gg.x, gg.y})), w1 = pack4(h1 * unpack4((u32x2){gg.z, gg.w}));
;                     *(u32x4*)(LO + o) = (u32x4){w0.x, w0.y, w1.x, w1.y}; }
	v_lshlrev_b32_e32 v14, 16, v18
	v_and_b32_e32 v15, 0xffff0000, v18
	v_lshlrev_b32_e32 v16, 16, v19
	v_and_b32_e32 v17, 0xffff0000, v19
	v_pk_mul_f32 v[16:17], v[4:5], v[16:17]
	v_pk_mul_f32 v[14:15], v[2:3], v[14:15]
	v_lshlrev_b32_e32 v18, 16, v21
	v_cvt_pk_bf16_f32 v14, v14, v15
	v_cvt_pk_bf16_f32 v15, v16, v17
	v_lshlrev_b32_e32 v16, 16, v20
	v_and_b32_e32 v17, 0xffff0000, v20
	v_and_b32_e32 v19, 0xffff0000, v21
	v_pk_mul_f32 v[18:19], v[8:9], v[18:19]
	v_pk_mul_f32 v[16:17], v[6:7], v[16:17]
	s_nop 0
	v_cvt_pk_bf16_f32 v16, v16, v17
	v_cvt_pk_bf16_f32 v17, v18, v19
	global_store_dwordx4 v[12:13], v[14:17], off offset:2048
	v_add_co_u32_e32 v12, vcc, s62, v10
	s_nop 1
	v_addc_co_u32_e32 v13, vcc, 0, v11, vcc
	global_load_dwordx4 v[14:17], v[12:13], off
	v_add_co_u32_e32 v36, vcc, s63, v10
	s_nop 1
	v_addc_co_u32_e32 v37, vcc, 0, v11, vcc
	v_add_co_u32_e32 v42, vcc, s74, v10
	global_load_dwordx4 v[18:21], v[36:37], off
	s_nop 0
	v_addc_co_u32_e32 v43, vcc, 0, v11, vcc
	global_load_dwordx4 v[44:47], v[42:43], off
	v_add_co_u32_e32 v10, vcc, s77, v10
	s_waitcnt vmcnt(1)
	v_lshlrev_b32_e32 v40, 16, v18
	v_addc_co_u32_e32 v11, vcc, 0, v11, vcc
	global_load_dwordx4 v[48:51], v[10:11], off
	v_lshlrev_b32_e32 v38, 16, v14
	v_and_b32_e32 v39, 0xffff0000, v14
	v_pk_mul_f32 v[38:39], v[28:29], v[38:39]
	v_lshlrev_b32_e32 v14, 16, v15
	v_mul_f32_e32 v1, 0x3fb8aa3b, v38
	v_exp_f32_e32 v38, v1
	v_mul_f32_e32 v1, 0x3fb8aa3b, v39
	v_exp_f32_e32 v39, v1
	v_and_b32_e32 v15, 0xffff0000, v15
	v_pk_mul_f32 v[14:15], v[26:27], v[14:15]
	v_xor_b32_e32 v66, 0x80000000, v38
	v_mul_f32_e32 v1, 0x3fb8aa3b, v14
	v_xor_b32_e32 v67, 0x80000000, v39
	v_exp_f32_e32 v14, v1
	v_mul_f32_e32 v1, 0x3fb8aa3b, v15
	v_pk_fma_f32 v[66:67], v[66:67], v[38:39], 1.0 op_sel_hi:[1,1,0]
	v_exp_f32_e32 v15, v1
	v_max_f32_e32 v1, 0, v66
	v_xor_b32_e32 v65, 0x80000000, v15
	v_xor_b32_e32 v64, 0x80000000, v14
	v_pk_fma_f32 v[64:65], v[64:65], v[14:15], 1.0 op_sel_hi:[1,1,0]
	v_and_b32_e32 v41, 0xffff0000, v18
	v_lshlrev_b32_e32 v18, 16, v19
	v_and_b32_e32 v19, 0xffff0000, v19
	s_waitcnt vmcnt(1)
	v_lshlrev_b32_e32 v62, 16, v44
	v_and_b32_e32 v63, 0xffff0000, v44
	v_lshlrev_b32_e32 v44, 16, v45
	v_sqrt_f32_e32 v66, v1
	v_max_f32_e32 v1, 0, v67
	v_and_b32_e32 v45, 0xffff0000, v45
	v_sqrt_f32_e32 v67, v1
	v_max_f32_e32 v1, 0, v64
	v_pk_mul_f32 v[40:41], v[66:67], v[40:41]
	v_pk_mul_f32 v[40:41], v[40:41], v[62:63]
	v_pk_fma_f32 v[2:3], v[2:3], v[38:39], v[40:41]
	v_lshlrev_b32_e32 v38, 16, v47
	v_and_b32_e32 v39, 0xffff0000, v47
	v_sqrt_f32_e32 v64, v1
	v_max_f32_e32 v1, 0, v65
	v_sqrt_f32_e32 v65, v1
	s_nop 0
	v_pk_mul_f32 v[18:19], v[64:65], v[18:19]
	s_nop 0
	v_pk_mul_f32 v[18:19], v[18:19], v[44:45]
	s_nop 0
	v_pk_fma_f32 v[40:41], v[4:5], v[14:15], v[18:19]
	v_lshlrev_b32_e32 v4, 16, v16
	v_and_b32_e32 v5, 0xffff0000, v16
	v_pk_mul_f32 v[4:5], v[32:33], v[4:5]
	v_lshlrev_b32_e32 v14, 16, v17
	v_mul_f32_e32 v1, 0x3fb8aa3b, v4
	v_exp_f32_e32 v4, v1
	v_mul_f32_e32 v1, 0x3fb8aa3b, v5
	v_exp_f32_e32 v5, v1
	v_and_b32_e32 v15, 0xffff0000, v17
	v_pk_mul_f32 v[14:15], v[30:31], v[14:15]
	v_lshlrev_b32_e32 v16, 16, v20
	v_and_b32_e32 v17, 0xffff0000, v20
	v_lshlrev_b32_e32 v18, 16, v21
	v_and_b32_e32 v19, 0xffff0000, v21
	v_lshlrev_b32_e32 v20, 16, v46
	v_and_b32_e32 v21, 0xffff0000, v46
	v_mul_f32_e32 v1, 0x3fb8aa3b, v14
	v_xor_b32_e32 v47, 0x80000000, v5
	v_xor_b32_e32 v46, 0x80000000, v4
	v_exp_f32_e32 v14, v1
	v_mul_f32_e32 v1, 0x3fb8aa3b, v15
	v_pk_fma_f32 v[46:47], v[46:47], v[4:5], 1.0 op_sel_hi:[1,1,0]
	v_exp_f32_e32 v15, v1
	v_max_f32_e32 v1, 0, v46
	v_xor_b32_e32 v45, 0x80000000, v15
	v_xor_b32_e32 v44, 0x80000000, v14
	v_pk_fma_f32 v[44:45], v[44:45], v[14:15], 1.0 op_sel_hi:[1,1,0]
	v_sqrt_f32_e32 v46, v1
	v_max_f32_e32 v1, 0, v47
	v_sqrt_f32_e32 v47, v1
	v_max_f32_e32 v1, 0, v44
	v_pk_mul_f32 v[16:17], v[46:47], v[16:17]
	v_pk_mul_f32 v[16:17], v[16:17], v[20:21]
	v_sqrt_f32_e32 v44, v1
	v_max_f32_e32 v1, 0, v45
	v_sqrt_f32_e32 v45, v1
	s_nop 0
	v_pk_mul_f32 v[18:19], v[44:45], v[18:19]
	s_nop 0
	v_pk_mul_f32 v[18:19], v[18:19], v[38:39]
	v_pk_fma_f32 v[38:39], v[6:7], v[4:5], v[16:17]
	s_waitcnt vmcnt(0)
; __device__ __forceinline__ f32x4 unpack4(u32x2 u) { return (f32x4){__uint_as_float(u.x << 16), __uint_as_float(u.x & 0xffff0000u), __uint_as_float(u.y << 16), __uint_as_float(u.y & 0xffff0000u)}; }
; __device__ __forceinline__ u32x2 pack4(f32x4 v) { u32x2 r; r.x = cvt_pk_bf16(v.x, v.y); r.y = cvt_pk_bf16(v.z, v.w); return r; }
; template <int ph>
; __device__ __forceinline__ void run_phase(const Args& args, LAS unsigned char* lds, const int G, const int bx, const bool fin = true) {
;     ...
;             auto lru_ab = [](f32x4 gr, f32x4 gi, f32x4 xc, f32x4 sp, f32x4& a, f32x4& bb) {
;                 const f32x4 la = gr * sp; a = (f32x4){__expf(la[0]), __expf(la[1]), __expf(la[2]), __expf(la[3])};
;                 const f32x4 om = (f32x4){1.f, 1.f, 1.f, 1.f} - a * a;
;                 bb = (f32x4){sqrtf(fmaxf(om[0], 0.f)), sqrtf(fmaxf(om[1], 0.f)), sqrtf(fmaxf(om[2], 0.f)), sqrtf(fmaxf(om[3], 0.f))} * gi * xc; };
;     ...
;                 for (int t = 0; t < 32; ++t) { const size_t o = base + (size_t)t * D;
;                     const u32x4 gr = *(const u32x4*)(GR + o), gi = *(const u32x4*)(GI + o), xc = *(const u32x4*)(XC + o), gg = *(const u32x4*)(GG + o);
;                     f32x4 a, bb;
;                     lru_ab(unpack4((u32x2){gr.x, gr.y}), unpack4((u32x2){gi.x, gi.y}), unpack4((u32x2){xc.x, xc.y}), sp0, a, bb); h0 = a * h0 + bb;
;                     lru_ab(unpack4((u32x2){gr.z, gr.w}), unpack4((u32x2){gi.z, gi.w}), unpack4((u32x2){xc.z, xc.w}), sp1, a, bb); h1 = a * h1 + bb;
;                     const u32x2 w0 = pack4(h0 * unpack4((u32x2){gg.x, gg.y})), w1 = pack4(h1 * unpack4((u32x2){gg.z, gg.w}));
;                     *(u32x4*)(LO + o) = (u32x4){w0.x, w0.y, w1.x, w1.y}; }
;                 if (seg == 63) { *(f32x4*)(out + O_PLRU + (size_t)b * D + ch) = h0; *(f32x4*)(out + O_PLRU + (size_t)b * D + ch + 4) = h1; }
	v_lshlrev_b32_e32 v4, 16, v48
	v_and_b32_e32 v5, 0xffff0000, v48
	v_lshlrev_b32_e32 v6, 16, v49
	v_and_b32_e32 v7, 0xffff0000, v49
	v_pk_mul_f32 v[6:7], v[40:41], v[6:7]
	v_pk_mul_f32 v[4:5], v[2:3], v[4:5]
	v_pk_fma_f32 v[8:9], v[8:9], v[14:15], v[18:19]
	v_cvt_pk_bf16_f32 v4, v4, v5
	v_cvt_pk_bf16_f32 v5, v6, v7
	v_lshlrev_b32_e32 v6, 16, v50
	v_and_b32_e32 v7, 0xffff0000, v50
	v_lshlrev_b32_e32 v14, 16, v51
	v_and_b32_e32 v15, 0xffff0000, v51
	v_pk_mul_f32 v[14:15], v[8:9], v[14:15]
	v_pk_mul_f32 v[6:7], v[38:39], v[6:7]
	s_nop 0
	v_cvt_pk_bf16_f32 v6, v6, v7
	v_cvt_pk_bf16_f32 v7, v14, v15
	global_store_dwordx4 v[36:37], v[4:7], off
	global_load_dwordx4 v[18:21], v[12:13], off offset:2048
	global_load_dwordx4 v[14:17], v[36:37], off offset:2048
	s_nop 0
	global_load_dwordx4 v[4:7], v[42:43], off offset:2048
	s_nop 0
	global_load_dwordx4 v[10:13], v[10:11], off offset:2048
	s_waitcnt vmcnt(3)
	v_lshlrev_b32_e32 v42, 16, v18
	v_and_b32_e32 v43, 0xffff0000, v18
	v_pk_mul_f32 v[42:43], v[28:29], v[42:43]
	v_lshlrev_b32_e32 v18, 16, v19
	v_mul_f32_e32 v1, 0x3fb8aa3b, v42
	v_exp_f32_e32 v42, v1
	v_mul_f32_e32 v1, 0x3fb8aa3b, v43
	v_exp_f32_e32 v43, v1
	v_and_b32_e32 v19, 0xffff0000, v19
	v_pk_mul_f32 v[18:19], v[26:27], v[18:19]
	v_xor_b32_e32 v50, 0x80000000, v42
	v_mul_f32_e32 v1, 0x3fb8aa3b, v18
	v_xor_b32_e32 v51, 0x80000000, v43
	v_exp_f32_e32 v18, v1
	v_mul_f32_e32 v1, 0x3fb8aa3b, v19
	v_pk_fma_f32 v[50:51], v[50:51], v[42:43], 1.0 op_sel_hi:[1,1,0]
	v_exp_f32_e32 v19, v1
	v_max_f32_e32 v1, 0, v50
	v_xor_b32_e32 v49, 0x80000000, v19
	v_xor_b32_e32 v48, 0x80000000, v18
	v_pk_fma_f32 v[48:49], v[48:49], v[18:19], 1.0 op_sel_hi:[1,1,0]
	s_waitcnt vmcnt(2)
	v_lshlrev_b32_e32 v44, 16, v14
	v_and_b32_e32 v45, 0xffff0000, v14
	v_lshlrev_b32_e32 v14, 16, v15
	v_and_b32_e32 v15, 0xffff0000, v15
	s_waitcnt vmcnt(1)
	v_lshlrev_b32_e32 v46, 16, v4
	v_and_b32_e32 v47, 0xffff0000, v4
	v_sqrt_f32_e32 v50, v1
	v_max_f32_e32 v1, 0, v51
	v_lshlrev_b32_e32 v4, 16, v5
	v_and_b32_e32 v5, 0xffff0000, v5
	v_sqrt_f32_e32 v51, v1
	v_max_f32_e32 v1, 0, v48
	v_pk_mul_f32 v[44:45], v[50:51], v[44:45]
	v_pk_mul_f32 v[44:45], v[44:45], v[46:47]
	v_pk_fma_f32 v[2:3], v[2:3], v[42:43], v[44:45]
	v_sqrt_f32_e32 v48, v1
	v_max_f32_e32 v1, 0, v49
	v_sqrt_f32_e32 v49, v1
	s_nop 0
	v_pk_mul_f32 v[14:15], v[48:49], v[14:15]
	s_nop 0
	v_pk_mul_f32 v[4:5], v[14:15], v[4:5]
	v_lshlrev_b32_e32 v14, 16, v20
	v_and_b32_e32 v15, 0xffff0000, v20
	v_pk_mul_f32 v[14:15], v[32:33], v[14:15]
	v_pk_fma_f32 v[4:5], v[40:41], v[18:19], v[4:5]
	v_mul_f32_e32 v1, 0x3fb8aa3b, v14
	v_exp_f32_e32 v14, v1
	v_mul_f32_e32 v1, 0x3fb8aa3b, v15
	v_exp_f32_e32 v15, v1
	v_lshlrev_b32_e32 v18, 16, v21
	v_and_b32_e32 v19, 0xffff0000, v21
	v_pk_mul_f32 v[18:19], v[30:31], v[18:19]
	v_xor_b32_e32 v45, 0x80000000, v15
	v_mul_f32_e32 v1, 0x3fb8aa3b, v18
	v_xor_b32_e32 v44, 0x80000000, v14
	v_exp_f32_e32 v18, v1
	v_mul_f32_e32 v1, 0x3fb8aa3b, v19
	v_pk_fma_f32 v[44:45], v[44:45], v[14:15], 1.0 op_sel_hi:[1,1,0]
	v_exp_f32_e32 v19, v1
	v_max_f32_e32 v1, 0, v44
	v_xor_b32_e32 v43, 0x80000000, v19
	v_xor_b32_e32 v42, 0x80000000, v18
	v_pk_fma_f32 v[42:43], v[42:43], v[18:19], 1.0 op_sel_hi:[1,1,0]
	v_lshlrev_b32_e32 v20, 16, v16
	v_and_b32_e32 v21, 0xffff0000, v16
	v_lshlrev_b32_e32 v16, 16, v17
	v_and_b32_e32 v17, 0xffff0000, v17
	v_lshlrev_b32_e32 v40, 16, v6
	v_and_b32_e32 v41, 0xffff0000, v6
	v_sqrt_f32_e32 v44, v1
	v_max_f32_e32 v1, 0, v45
	v_lshlrev_b32_e32 v6, 16, v7
	v_and_b32_e32 v7, 0xffff0000, v7
	v_sqrt_f32_e32 v45, v1
	v_max_f32_e32 v1, 0, v42
	v_pk_mul_f32 v[20:21], v[44:45], v[20:21]
	v_pk_mul_f32 v[20:21], v[20:21], v[40:41]
	v_sqrt_f32_e32 v42, v1
	v_max_f32_e32 v1, 0, v43
	v_sqrt_f32_e32 v43, v1
	s_nop 0
	v_pk_mul_f32 v[16:17], v[42:43], v[16:17]
	s_nop 0
	v_pk_mul_f32 v[6:7], v[16:17], v[6:7]
	s_nop 0
	v_pk_fma_f32 v[8:9], v[8:9], v[18:19], v[6:7]
	v_pk_fma_f32 v[6:7], v[38:39], v[14:15], v[20:21]
	s_waitcnt vmcnt(0)
	v_lshlrev_b32_e32 v14, 16, v10
	v_and_b32_e32 v15, 0xffff0000, v10
	v_lshlrev_b32_e32 v10, 16, v11
	v_and_b32_e32 v11, 0xffff0000, v11
	v_pk_mul_f32 v[16:17], v[4:5], v[10:11]
	v_pk_mul_f32 v[10:11], v[2:3], v[14:15]
	v_lshlrev_b32_e32 v14, 16, v12
	v_and_b32_e32 v15, 0xffff0000, v12
	v_lshlrev_b32_e32 v12, 16, v13
	v_and_b32_e32 v13, 0xffff0000, v13
	v_cvt_pk_bf16_f32 v10, v10, v11
	v_cvt_pk_bf16_f32 v11, v16, v17
	v_pk_mul_f32 v[16:17], v[8:9], v[12:13]
	v_pk_mul_f32 v[12:13], v[6:7], v[14:15]
	s_nop 0
	v_cvt_pk_bf16_f32 v12, v12, v13
	v_cvt_pk_bf16_f32 v13, v16, v17
	global_store_dwordx4 v[36:37], v[10:13], off offset:2048
	s_cbranch_scc0 .LBB0_1073
	s_and_saveexec_b64 s[0:1], s[4:5]
	s_cbranch_execz .LBB0_1043
	s_lshl_b64 s[10:11], s[22:23], 12
	s_add_u32 s10, s59, s10
	s_addc_u32 s11, s60, s11
	global_store_dwordx4 v60, v[2:5], s[10:11]
	global_store_dwordx4 v60, v[6:9], s[10:11] offset:16
	s_branch .LBB0_1043
